# gnorm: every wave issues all 32 loads of its 4 rows up front (was 8 in flight, each row waiting on the previous row's store acks), DPP reductions as 8 interleaved chains
# speedup vs baseline: 1.0016x; 1.0016x over previous
; #define GAS __attribute__((address_space(1)))
; __device__ __forceinline__ gws_t launder_s(const void* p0) { unsigned char* p = (unsigned char*)p0; asm volatile("" : "+s"(p)); return (gws_t)p; }
; __device__ __forceinline__ int launder_v(int v) { asm volatile("" : "+v"(v)); return v; }
; __device__ __forceinline__ int grid_x() { int g = (int)gridDim.x; asm volatile("" : "+s"(g)); return g; }
; __device__ __forceinline__ void unpack8(const v4u v, float (&f)[8]) { f[0] = bflo(v.x); f[1] = bfhi(v.x); f[2] = bflo(v.y); f[3] = bfhi(v.y); f[4] = bflo(v.z); f[5] = bfhi(v.z); f[6] = bflo(v.w); f[7] = bfhi(v.w); }
; __device__ __forceinline__ void phase_gnorm(const Params& P, int seg) {
;     GAS bf16* ypre = (GAS bf16*)(launder_s(P.ws) + WS_YPRE);
;     const int tidl = launder_v(threadIdx.x); const int lane = tidl & 63, gw = blockIdx.x * 8 + (tidl >> 6), NGW = grid_x() * 8;
;     const int nrows = (seg == 0) ? RS + 16 : RS;
;     for (int rr = gw; rr < nrows; rr += NGW) { const int row = (rr < RS) ? rr : rr + 48; GAS bf16* p = ypre + (size_t)row * DINNER + lane * 8;
;         v4u raw[8];
; #pragma unroll
;         for (int g = 0; g < 8; ++g) raw[g] = *(const GAS v4u*)(p + g * 512);
; #pragma unroll
;         for (int g = 0; g < 8; ++g) { float f[8]; unpack8(raw[g], f); float s = 0.f;
.Lgn_fast:
	s_mov_b64 exec, -1
	v_and_b32_e32 v24, 63, v172
	v_lshlrev_b32_e32 v24, 4, v24
	v_add_u32_e32 v25, 0x1000, v24
	v_readfirstlane_b32 s63, v172
	v_readlane_b32 s65, v254, 38
	s_nop 3
	s_lshr_b32 s63, s63, 6
	s_lshl_b32 s53, s2, 3
	s_add_i32 s63, s63, s53
	s_add_u32 s40, s80, 0x304f1000
	s_addc_u32 s41, s81, 0
	s_lshl_b32 s53, s63, 13
	s_add_u32 s54, s40, s53
	s_addc_u32 s55, s41, 0
	s_add_u32 s56, s54, 0x1000000
	s_addc_u32 s57, s55, 0
	s_add_u32 s60, s56, 0x1000000
	s_addc_u32 s61, s57, 0
	s_add_u32 s66, s60, 0x1000000
	s_addc_u32 s67, s61, 0
	global_load_dwordx4 v[40:43], v24, s[54:55]
	global_load_dwordx4 v[44:47], v24, s[54:55] offset:1024
	global_load_dwordx4 v[48:51], v24, s[54:55] offset:2048
	global_load_dwordx4 v[52:55], v24, s[54:55] offset:3072
	global_load_dwordx4 v[56:59], v25, s[54:55]
	global_load_dwordx4 v[60:63], v25, s[54:55] offset:1024
	global_load_dwordx4 v[64:67], v25, s[54:55] offset:2048
	global_load_dwordx4 v[68:71], v25, s[54:55] offset:3072
	global_load_dwordx4 v[72:75], v24, s[56:57]
	global_load_dwordx4 v[76:79], v24, s[56:57] offset:1024
	global_load_dwordx4 v[80:83], v24, s[56:57] offset:2048
	global_load_dwordx4 v[84:87], v24, s[56:57] offset:3072
	global_load_dwordx4 v[88:91], v25, s[56:57]
	global_load_dwordx4 v[92:95], v25, s[56:57] offset:1024
	global_load_dwordx4 v[96:99], v25, s[56:57] offset:2048
	global_load_dwordx4 v[100:103], v25, s[56:57] offset:3072
	global_load_dwordx4 v[120:123], v24, s[60:61]
	global_load_dwordx4 v[124:127], v24, s[60:61] offset:1024
	global_load_dwordx4 v[128:131], v24, s[60:61] offset:2048
	global_load_dwordx4 v[132:135], v24, s[60:61] offset:3072
	global_load_dwordx4 v[136:139], v25, s[60:61]
	global_load_dwordx4 v[140:143], v25, s[60:61] offset:1024
	global_load_dwordx4 v[144:147], v25, s[60:61] offset:2048
	global_load_dwordx4 v[148:151], v25, s[60:61] offset:3072
	global_load_dwordx4 v[184:187], v24, s[66:67]
	global_load_dwordx4 v[188:191], v24, s[66:67] offset:1024
	global_load_dwordx4 v[192:195], v24, s[66:67] offset:2048
	global_load_dwordx4 v[196:199], v24, s[66:67] offset:3072
	global_load_dwordx4 v[200:203], v25, s[66:67]
	global_load_dwordx4 v[204:207], v25, s[66:67] offset:1024
	global_load_dwordx4 v[208:211], v25, s[66:67] offset:2048
	global_load_dwordx4 v[212:215], v25, s[66:67] offset:3072
	s_waitcnt vmcnt(24)
	v_lshlrev_b32_e32 v4, 16, v40
	v_and_b32_e32 v5, 0xffff0000, v40
	v_mul_f32_e32 v8, v4, v4
	v_fmac_f32_e32 v8, v5, v5
	v_lshlrev_b32_e32 v4, 16, v41
	v_and_b32_e32 v5, 0xffff0000, v41
	v_fmac_f32_e32 v8, v4, v4
	v_fmac_f32_e32 v8, v5, v5
	v_lshlrev_b32_e32 v4, 16, v42
	v_and_b32_e32 v5, 0xffff0000, v42
	v_fmac_f32_e32 v8, v4, v4
	v_fmac_f32_e32 v8, v5, v5
	v_lshlrev_b32_e32 v4, 16, v43
	v_and_b32_e32 v5, 0xffff0000, v43
	v_fmac_f32_e32 v8, v4, v4
	v_fmac_f32_e32 v8, v5, v5
	v_lshlrev_b32_e32 v4, 16, v44
	v_and_b32_e32 v5, 0xffff0000, v44
	v_mul_f32_e32 v9, v4, v4
	v_fmac_f32_e32 v9, v5, v5
	v_lshlrev_b32_e32 v4, 16, v45
	v_and_b32_e32 v5, 0xffff0000, v45
	v_fmac_f32_e32 v9, v4, v4
	v_fmac_f32_e32 v9, v5, v5
	v_lshlrev_b32_e32 v4, 16, v46
	v_and_b32_e32 v5, 0xffff0000, v46
	v_fmac_f32_e32 v9, v4, v4
	v_fmac_f32_e32 v9, v5, v5
	v_lshlrev_b32_e32 v4, 16, v47
	v_and_b32_e32 v5, 0xffff0000, v47
	v_fmac_f32_e32 v9, v4, v4
	v_fmac_f32_e32 v9, v5, v5
	v_lshlrev_b32_e32 v4, 16, v48
	v_and_b32_e32 v5, 0xffff0000, v48
	v_mul_f32_e32 v10, v4, v4
	v_fmac_f32_e32 v10, v5, v5
	v_lshlrev_b32_e32 v4, 16, v49
	v_and_b32_e32 v5, 0xffff0000, v49
	v_fmac_f32_e32 v10, v4, v4
	v_fmac_f32_e32 v10, v5, v5
	v_lshlrev_b32_e32 v4, 16, v50
	v_and_b32_e32 v5, 0xffff0000, v50
	v_fmac_f32_e32 v10, v4, v4
	v_fmac_f32_e32 v10, v5, v5
	v_lshlrev_b32_e32 v4, 16, v51
	v_and_b32_e32 v5, 0xffff0000, v51
	v_fmac_f32_e32 v10, v4, v4
	v_fmac_f32_e32 v10, v5, v5
	v_lshlrev_b32_e32 v4, 16, v52
	v_and_b32_e32 v5, 0xffff0000, v52
	v_mul_f32_e32 v11, v4, v4
	v_fmac_f32_e32 v11, v5, v5
	v_lshlrev_b32_e32 v4, 16, v53
	v_and_b32_e32 v5, 0xffff0000, v53
	v_fmac_f32_e32 v11, v4, v4
	v_fmac_f32_e32 v11, v5, v5
	v_lshlrev_b32_e32 v4, 16, v54
	v_and_b32_e32 v5, 0xffff0000, v54
	v_fmac_f32_e32 v11, v4, v4
	v_fmac_f32_e32 v11, v5, v5
	v_lshlrev_b32_e32 v4, 16, v55
	v_and_b32_e32 v5, 0xffff0000, v55
	v_fmac_f32_e32 v11, v4, v4
	v_fmac_f32_e32 v11, v5, v5
	v_lshlrev_b32_e32 v4, 16, v56
	v_and_b32_e32 v5, 0xffff0000, v56
	v_mul_f32_e32 v12, v4, v4
	v_fmac_f32_e32 v12, v5, v5
	v_lshlrev_b32_e32 v4, 16, v57
	v_and_b32_e32 v5, 0xffff0000, v57
	v_fmac_f32_e32 v12, v4, v4
	v_fmac_f32_e32 v12, v5, v5
	v_lshlrev_b32_e32 v4, 16, v58
	v_and_b32_e32 v5, 0xffff0000, v58
	v_fmac_f32_e32 v12, v4, v4
	v_fmac_f32_e32 v12, v5, v5
	v_lshlrev_b32_e32 v4, 16, v59
	v_and_b32_e32 v5, 0xffff0000, v59
	v_fmac_f32_e32 v12, v4, v4
	v_fmac_f32_e32 v12, v5, v5
	v_lshlrev_b32_e32 v4, 16, v60
	v_and_b32_e32 v5, 0xffff0000, v60
	v_mul_f32_e32 v13, v4, v4
	v_fmac_f32_e32 v13, v5, v5
	v_lshlrev_b32_e32 v4, 16, v61
	v_and_b32_e32 v5, 0xffff0000, v61
	v_fmac_f32_e32 v13, v4, v4
	v_fmac_f32_e32 v13, v5, v5
	v_lshlrev_b32_e32 v4, 16, v62
	v_and_b32_e32 v5, 0xffff0000, v62
	v_fmac_f32_e32 v13, v4, v4
	v_fmac_f32_e32 v13, v5, v5
	v_lshlrev_b32_e32 v4, 16, v63
	v_and_b32_e32 v5, 0xffff0000, v63
	v_fmac_f32_e32 v13, v4, v4
	v_fmac_f32_e32 v13, v5, v5
	v_lshlrev_b32_e32 v4, 16, v64
	v_and_b32_e32 v5, 0xffff0000, v64
	v_mul_f32_e32 v14, v4, v4
	v_fmac_f32_e32 v14, v5, v5
	v_lshlrev_b32_e32 v4, 16, v65
	v_and_b32_e32 v5, 0xffff0000, v65
	v_fmac_f32_e32 v14, v4, v4
	v_fmac_f32_e32 v14, v5, v5
	v_lshlrev_b32_e32 v4, 16, v66
	v_and_b32_e32 v5, 0xffff0000, v66
	v_fmac_f32_e32 v14, v4, v4
	v_fmac_f32_e32 v14, v5, v5
	v_lshlrev_b32_e32 v4, 16, v67
; #define GAS __attribute__((address_space(1)))
; __device__ __forceinline__ void unpack8(const v4u v, float (&f)[8]) { f[0] = bflo(v.x); f[1] = bfhi(v.x); f[2] = bflo(v.y); f[3] = bfhi(v.y); f[4] = bflo(v.z); f[5] = bfhi(v.z); f[6] = bflo(v.w); f[7] = bfhi(v.w); }
; __device__ __forceinline__ v4u pack8(const float (&f)[8]) { v4u o; o.x = cvt_pk_bf16(f[0], f[1]); o.y = cvt_pk_bf16(f[2], f[3]); o.z = cvt_pk_bf16(f[4], f[5]); o.w = cvt_pk_bf16(f[6], f[7]); return o; }
; __device__ __forceinline__ float wave_sum(float v) {
; #pragma unroll
;     for (int o = 1; o < 64; o <<= 1) v += __shfl_xor(v, o);
;     return v;
; }
; __device__ __forceinline__ void phase_gnorm(const Params& P, int seg) {
;     ...
;         for (int g = 0; g < 8; ++g) { float f[8]; unpack8(raw[g], f); float s = 0.f;
; #pragma unroll
;             for (int e = 0; e < 8; ++e) s += f[e] * f[e];
;             s = wave_sum(s); const float rs = rsqrtf(s * (1.f / 512.f) + EPS);
; #pragma unroll
;             for (int e = 0; e < 8; ++e) f[e] *= rs;
;             *(GAS v4u*)(p + g * 512) = pack8(f); } }
	v_and_b32_e32 v5, 0xffff0000, v67
	v_fmac_f32_e32 v14, v4, v4
	v_fmac_f32_e32 v14, v5, v5
	v_lshlrev_b32_e32 v4, 16, v68
	v_and_b32_e32 v5, 0xffff0000, v68
	v_mul_f32_e32 v15, v4, v4
	v_fmac_f32_e32 v15, v5, v5
	v_lshlrev_b32_e32 v4, 16, v69
	v_and_b32_e32 v5, 0xffff0000, v69
	v_fmac_f32_e32 v15, v4, v4
	v_fmac_f32_e32 v15, v5, v5
	v_lshlrev_b32_e32 v4, 16, v70
	v_and_b32_e32 v5, 0xffff0000, v70
	v_fmac_f32_e32 v15, v4, v4
	v_fmac_f32_e32 v15, v5, v5
	v_lshlrev_b32_e32 v4, 16, v71
	v_and_b32_e32 v5, 0xffff0000, v71
	v_fmac_f32_e32 v15, v4, v4
	v_fmac_f32_e32 v15, v5, v5
	v_add_f32_dpp v8, v8, v8 quad_perm:[1,0,3,2] row_mask:0xf bank_mask:0xf
	v_add_f32_dpp v9, v9, v9 quad_perm:[1,0,3,2] row_mask:0xf bank_mask:0xf
	v_add_f32_dpp v10, v10, v10 quad_perm:[1,0,3,2] row_mask:0xf bank_mask:0xf
	v_add_f32_dpp v11, v11, v11 quad_perm:[1,0,3,2] row_mask:0xf bank_mask:0xf
	v_add_f32_dpp v12, v12, v12 quad_perm:[1,0,3,2] row_mask:0xf bank_mask:0xf
	v_add_f32_dpp v13, v13, v13 quad_perm:[1,0,3,2] row_mask:0xf bank_mask:0xf
	v_add_f32_dpp v14, v14, v14 quad_perm:[1,0,3,2] row_mask:0xf bank_mask:0xf
	v_add_f32_dpp v15, v15, v15 quad_perm:[1,0,3,2] row_mask:0xf bank_mask:0xf
	v_add_f32_dpp v8, v8, v8 quad_perm:[2,3,0,1] row_mask:0xf bank_mask:0xf
	v_add_f32_dpp v9, v9, v9 quad_perm:[2,3,0,1] row_mask:0xf bank_mask:0xf
	v_add_f32_dpp v10, v10, v10 quad_perm:[2,3,0,1] row_mask:0xf bank_mask:0xf
	v_add_f32_dpp v11, v11, v11 quad_perm:[2,3,0,1] row_mask:0xf bank_mask:0xf
	v_add_f32_dpp v12, v12, v12 quad_perm:[2,3,0,1] row_mask:0xf bank_mask:0xf
	v_add_f32_dpp v13, v13, v13 quad_perm:[2,3,0,1] row_mask:0xf bank_mask:0xf
	v_add_f32_dpp v14, v14, v14 quad_perm:[2,3,0,1] row_mask:0xf bank_mask:0xf
	v_add_f32_dpp v15, v15, v15 quad_perm:[2,3,0,1] row_mask:0xf bank_mask:0xf
	v_add_f32_dpp v8, v8, v8 row_half_mirror row_mask:0xf bank_mask:0xf
	v_add_f32_dpp v9, v9, v9 row_half_mirror row_mask:0xf bank_mask:0xf
	v_add_f32_dpp v10, v10, v10 row_half_mirror row_mask:0xf bank_mask:0xf
	v_add_f32_dpp v11, v11, v11 row_half_mirror row_mask:0xf bank_mask:0xf
	v_add_f32_dpp v12, v12, v12 row_half_mirror row_mask:0xf bank_mask:0xf
	v_add_f32_dpp v13, v13, v13 row_half_mirror row_mask:0xf bank_mask:0xf
	v_add_f32_dpp v14, v14, v14 row_half_mirror row_mask:0xf bank_mask:0xf
	v_add_f32_dpp v15, v15, v15 row_half_mirror row_mask:0xf bank_mask:0xf
	v_add_f32_dpp v8, v8, v8 row_mirror row_mask:0xf bank_mask:0xf
	v_add_f32_dpp v9, v9, v9 row_mirror row_mask:0xf bank_mask:0xf
	v_add_f32_dpp v10, v10, v10 row_mirror row_mask:0xf bank_mask:0xf
	v_add_f32_dpp v11, v11, v11 row_mirror row_mask:0xf bank_mask:0xf
	v_add_f32_dpp v12, v12, v12 row_mirror row_mask:0xf bank_mask:0xf
	v_add_f32_dpp v13, v13, v13 row_mirror row_mask:0xf bank_mask:0xf
	v_add_f32_dpp v14, v14, v14 row_mirror row_mask:0xf bank_mask:0xf
	v_add_f32_dpp v15, v15, v15 row_mirror row_mask:0xf bank_mask:0xf
	v_add_f32_dpp v8, v8, v8 row_bcast:15 row_mask:0xa bank_mask:0xf
	v_add_f32_dpp v9, v9, v9 row_bcast:15 row_mask:0xa bank_mask:0xf
	v_add_f32_dpp v10, v10, v10 row_bcast:15 row_mask:0xa bank_mask:0xf
	v_add_f32_dpp v11, v11, v11 row_bcast:15 row_mask:0xa bank_mask:0xf
	v_add_f32_dpp v12, v12, v12 row_bcast:15 row_mask:0xa bank_mask:0xf
	v_add_f32_dpp v13, v13, v13 row_bcast:15 row_mask:0xa bank_mask:0xf
	v_add_f32_dpp v14, v14, v14 row_bcast:15 row_mask:0xa bank_mask:0xf
	v_add_f32_dpp v15, v15, v15 row_bcast:15 row_mask:0xa bank_mask:0xf
	v_add_f32_dpp v8, v8, v8 row_bcast:31 row_mask:0xc bank_mask:0xf
	v_add_f32_dpp v9, v9, v9 row_bcast:31 row_mask:0xc bank_mask:0xf
	v_add_f32_dpp v10, v10, v10 row_bcast:31 row_mask:0xc bank_mask:0xf
	v_add_f32_dpp v11, v11, v11 row_bcast:31 row_mask:0xc bank_mask:0xf
	v_add_f32_dpp v12, v12, v12 row_bcast:31 row_mask:0xc bank_mask:0xf
	v_add_f32_dpp v13, v13, v13 row_bcast:31 row_mask:0xc bank_mask:0xf
	v_add_f32_dpp v14, v14, v14 row_bcast:31 row_mask:0xc bank_mask:0xf
	v_add_f32_dpp v15, v15, v15 row_bcast:31 row_mask:0xc bank_mask:0xf
	s_nop 1
	v_readlane_b32 s68, v8, 63
	v_readlane_b32 s69, v9, 63
	v_readlane_b32 s70, v10, 63
	v_readlane_b32 s71, v11, 63
	v_readlane_b32 s72, v12, 63
	v_readlane_b32 s73, v13, 63
	v_readlane_b32 s74, v14, 63
	v_readlane_b32 s75, v15, 63
	s_nop 1
	v_mov_b32_e32 v16, s68
	v_mov_b32_e32 v17, s69
	v_mov_b32_e32 v18, s70
	v_mov_b32_e32 v19, s71
	v_mov_b32_e32 v20, s72
	v_mov_b32_e32 v21, s73
	v_mov_b32_e32 v22, s74
	v_mov_b32_e32 v23, s75
	v_fmamk_f32 v16, v16, 0x3b000000, v176
	v_fmamk_f32 v17, v17, 0x3b000000, v176
	v_fmamk_f32 v18, v18, 0x3b000000, v176
	v_fmamk_f32 v19, v19, 0x3b000000, v176
	v_fmamk_f32 v20, v20, 0x3b000000, v176
	v_fmamk_f32 v21, v21, 0x3b000000, v176
	v_fmamk_f32 v22, v22, 0x3b000000, v176
	v_fmamk_f32 v23, v23, 0x3b000000, v176
	v_rsq_f32_e32 v16, v16
	v_rsq_f32_e32 v17, v17
	v_rsq_f32_e32 v18, v18
	v_rsq_f32_e32 v19, v19
	v_rsq_f32_e32 v20, v20
	v_rsq_f32_e32 v21, v21
	v_rsq_f32_e32 v22, v22
	v_rsq_f32_e32 v23, v23
	v_lshlrev_b32_e32 v4, 16, v40
	v_and_b32_e32 v5, 0xffff0000, v40
	v_mul_f32_e32 v4, v16, v4
	v_mul_f32_e32 v5, v16, v5
	v_cvt_pk_bf16_f32 v40, v4, v5
	v_lshlrev_b32_e32 v4, 16, v41
	v_and_b32_e32 v5, 0xffff0000, v41
	v_mul_f32_e32 v4, v16, v4
	v_mul_f32_e32 v5, v16, v5
	v_cvt_pk_bf16_f32 v41, v4, v5
	v_lshlrev_b32_e32 v4, 16, v42
	v_and_b32_e32 v5, 0xffff0000, v42
	v_mul_f32_e32 v4, v16, v4
	v_mul_f32_e32 v5, v16, v5
	v_cvt_pk_bf16_f32 v42, v4, v5
	v_lshlrev_b32_e32 v4, 16, v43
	v_and_b32_e32 v5, 0xffff0000, v43
	v_mul_f32_e32 v4, v16, v4
	v_mul_f32_e32 v5, v16, v5
	v_cvt_pk_bf16_f32 v43, v4, v5
	global_store_dwordx4 v24, v[40:43], s[54:55]
	v_lshlrev_b32_e32 v4, 16, v44
	v_and_b32_e32 v5, 0xffff0000, v44
; #define GAS __attribute__((address_space(1)))
; __device__ __forceinline__ v4u pack8(const float (&f)[8]) { v4u o; o.x = cvt_pk_bf16(f[0], f[1]); o.y = cvt_pk_bf16(f[2], f[3]); o.z = cvt_pk_bf16(f[4], f[5]); o.w = cvt_pk_bf16(f[6], f[7]); return o; }
; __device__ __forceinline__ void phase_gnorm(const Params& P, int seg) {
;     ...
; #pragma unroll
;             for (int e = 0; e < 8; ++e) f[e] *= rs;
;             *(GAS v4u*)(p + g * 512) = pack8(f); } }
	v_mul_f32_e32 v4, v17, v4
	v_mul_f32_e32 v5, v17, v5
	v_cvt_pk_bf16_f32 v44, v4, v5
	v_lshlrev_b32_e32 v4, 16, v45
	v_and_b32_e32 v5, 0xffff0000, v45
	v_mul_f32_e32 v4, v17, v4
	v_mul_f32_e32 v5, v17, v5
	v_cvt_pk_bf16_f32 v45, v4, v5
	v_lshlrev_b32_e32 v4, 16, v46
	v_and_b32_e32 v5, 0xffff0000, v46
	v_mul_f32_e32 v4, v17, v4
	v_mul_f32_e32 v5, v17, v5
	v_cvt_pk_bf16_f32 v46, v4, v5
	v_lshlrev_b32_e32 v4, 16, v47
	v_and_b32_e32 v5, 0xffff0000, v47
	v_mul_f32_e32 v4, v17, v4
	v_mul_f32_e32 v5, v17, v5
	v_cvt_pk_bf16_f32 v47, v4, v5
	global_store_dwordx4 v24, v[44:47], s[54:55] offset:1024
	v_lshlrev_b32_e32 v4, 16, v48
	v_and_b32_e32 v5, 0xffff0000, v48
	v_mul_f32_e32 v4, v18, v4
	v_mul_f32_e32 v5, v18, v5
	v_cvt_pk_bf16_f32 v48, v4, v5
	v_lshlrev_b32_e32 v4, 16, v49
	v_and_b32_e32 v5, 0xffff0000, v49
	v_mul_f32_e32 v4, v18, v4
	v_mul_f32_e32 v5, v18, v5
	v_cvt_pk_bf16_f32 v49, v4, v5
	v_lshlrev_b32_e32 v4, 16, v50
	v_and_b32_e32 v5, 0xffff0000, v50
	v_mul_f32_e32 v4, v18, v4
	v_mul_f32_e32 v5, v18, v5
	v_cvt_pk_bf16_f32 v50, v4, v5
	v_lshlrev_b32_e32 v4, 16, v51
	v_and_b32_e32 v5, 0xffff0000, v51
	v_mul_f32_e32 v4, v18, v4
	v_mul_f32_e32 v5, v18, v5
	v_cvt_pk_bf16_f32 v51, v4, v5
	global_store_dwordx4 v24, v[48:51], s[54:55] offset:2048
	v_lshlrev_b32_e32 v4, 16, v52
	v_and_b32_e32 v5, 0xffff0000, v52
	v_mul_f32_e32 v4, v19, v4
	v_mul_f32_e32 v5, v19, v5
	v_cvt_pk_bf16_f32 v52, v4, v5
	v_lshlrev_b32_e32 v4, 16, v53
	v_and_b32_e32 v5, 0xffff0000, v53
	v_mul_f32_e32 v4, v19, v4
	v_mul_f32_e32 v5, v19, v5
	v_cvt_pk_bf16_f32 v53, v4, v5
	v_lshlrev_b32_e32 v4, 16, v54
	v_and_b32_e32 v5, 0xffff0000, v54
	v_mul_f32_e32 v4, v19, v4
	v_mul_f32_e32 v5, v19, v5
	v_cvt_pk_bf16_f32 v54, v4, v5
	v_lshlrev_b32_e32 v4, 16, v55
	v_and_b32_e32 v5, 0xffff0000, v55
	v_mul_f32_e32 v4, v19, v4
	v_mul_f32_e32 v5, v19, v5
	v_cvt_pk_bf16_f32 v55, v4, v5
	global_store_dwordx4 v24, v[52:55], s[54:55] offset:3072
	v_lshlrev_b32_e32 v4, 16, v56
	v_and_b32_e32 v5, 0xffff0000, v56
	v_mul_f32_e32 v4, v20, v4
	v_mul_f32_e32 v5, v20, v5
	v_cvt_pk_bf16_f32 v56, v4, v5
	v_lshlrev_b32_e32 v4, 16, v57
	v_and_b32_e32 v5, 0xffff0000, v57
	v_mul_f32_e32 v4, v20, v4
	v_mul_f32_e32 v5, v20, v5
	v_cvt_pk_bf16_f32 v57, v4, v5
	v_lshlrev_b32_e32 v4, 16, v58
	v_and_b32_e32 v5, 0xffff0000, v58
	v_mul_f32_e32 v4, v20, v4
	v_mul_f32_e32 v5, v20, v5
	v_cvt_pk_bf16_f32 v58, v4, v5
	v_lshlrev_b32_e32 v4, 16, v59
	v_and_b32_e32 v5, 0xffff0000, v59
	v_mul_f32_e32 v4, v20, v4
	v_mul_f32_e32 v5, v20, v5
	v_cvt_pk_bf16_f32 v59, v4, v5
	global_store_dwordx4 v25, v[56:59], s[54:55]
	v_lshlrev_b32_e32 v4, 16, v60
	v_and_b32_e32 v5, 0xffff0000, v60
	v_mul_f32_e32 v4, v21, v4
	v_mul_f32_e32 v5, v21, v5
	v_cvt_pk_bf16_f32 v60, v4, v5
	v_lshlrev_b32_e32 v4, 16, v61
	v_and_b32_e32 v5, 0xffff0000, v61
	v_mul_f32_e32 v4, v21, v4
	v_mul_f32_e32 v5, v21, v5
	v_cvt_pk_bf16_f32 v61, v4, v5
	v_lshlrev_b32_e32 v4, 16, v62
	v_and_b32_e32 v5, 0xffff0000, v62
	v_mul_f32_e32 v4, v21, v4
	v_mul_f32_e32 v5, v21, v5
	v_cvt_pk_bf16_f32 v62, v4, v5
	v_lshlrev_b32_e32 v4, 16, v63
	v_and_b32_e32 v5, 0xffff0000, v63
	v_mul_f32_e32 v4, v21, v4
	v_mul_f32_e32 v5, v21, v5
	v_cvt_pk_bf16_f32 v63, v4, v5
	global_store_dwordx4 v25, v[60:63], s[54:55] offset:1024
	v_lshlrev_b32_e32 v4, 16, v64
	v_and_b32_e32 v5, 0xffff0000, v64
	v_mul_f32_e32 v4, v22, v4
	v_mul_f32_e32 v5, v22, v5
	v_cvt_pk_bf16_f32 v64, v4, v5
	v_lshlrev_b32_e32 v4, 16, v65
	v_and_b32_e32 v5, 0xffff0000, v65
	v_mul_f32_e32 v4, v22, v4
	v_mul_f32_e32 v5, v22, v5
	v_cvt_pk_bf16_f32 v65, v4, v5
	v_lshlrev_b32_e32 v4, 16, v66
	v_and_b32_e32 v5, 0xffff0000, v66
	v_mul_f32_e32 v4, v22, v4
	v_mul_f32_e32 v5, v22, v5
	v_cvt_pk_bf16_f32 v66, v4, v5
	v_lshlrev_b32_e32 v4, 16, v67
	v_and_b32_e32 v5, 0xffff0000, v67
	v_mul_f32_e32 v4, v22, v4
	v_mul_f32_e32 v5, v22, v5
	v_cvt_pk_bf16_f32 v67, v4, v5
	global_store_dwordx4 v25, v[64:67], s[54:55] offset:2048
	v_lshlrev_b32_e32 v4, 16, v68
	v_and_b32_e32 v5, 0xffff0000, v68
	v_mul_f32_e32 v4, v23, v4
	v_mul_f32_e32 v5, v23, v5
	v_cvt_pk_bf16_f32 v68, v4, v5
	v_lshlrev_b32_e32 v4, 16, v69
	v_and_b32_e32 v5, 0xffff0000, v69
	v_mul_f32_e32 v4, v23, v4
	v_mul_f32_e32 v5, v23, v5
	v_cvt_pk_bf16_f32 v69, v4, v5
	v_lshlrev_b32_e32 v4, 16, v70
	v_and_b32_e32 v5, 0xffff0000, v70
	v_mul_f32_e32 v4, v23, v4
	v_mul_f32_e32 v5, v23, v5
	v_cvt_pk_bf16_f32 v70, v4, v5
	v_lshlrev_b32_e32 v4, 16, v71
	v_and_b32_e32 v5, 0xffff0000, v71
	v_mul_f32_e32 v4, v23, v4
	v_mul_f32_e32 v5, v23, v5
	v_cvt_pk_bf16_f32 v71, v4, v5
	global_store_dwordx4 v25, v[68:71], s[54:55] offset:3072
	s_waitcnt vmcnt(24)
; __device__ __forceinline__ void unpack8(const v4u v, float (&f)[8]) { f[0] = bflo(v.x); f[1] = bfhi(v.x); f[2] = bflo(v.y); f[3] = bfhi(v.y); f[4] = bflo(v.z); f[5] = bfhi(v.z); f[6] = bflo(v.w); f[7] = bfhi(v.w); }
; __device__ __forceinline__ void phase_gnorm(const Params& P, int seg) {
;     ...
;         for (int g = 0; g < 8; ++g) { float f[8]; unpack8(raw[g], f); float s = 0.f;
; #pragma unroll
;             for (int e = 0; e < 8; ++e) s += f[e] * f[e];
	v_lshlrev_b32_e32 v4, 16, v72
	v_and_b32_e32 v5, 0xffff0000, v72
	v_mul_f32_e32 v8, v4, v4
	v_fmac_f32_e32 v8, v5, v5
	v_lshlrev_b32_e32 v4, 16, v73
	v_and_b32_e32 v5, 0xffff0000, v73
	v_fmac_f32_e32 v8, v4, v4
	v_fmac_f32_e32 v8, v5, v5
	v_lshlrev_b32_e32 v4, 16, v74
	v_and_b32_e32 v5, 0xffff0000, v74
	v_fmac_f32_e32 v8, v4, v4
	v_fmac_f32_e32 v8, v5, v5
	v_lshlrev_b32_e32 v4, 16, v75
	v_and_b32_e32 v5, 0xffff0000, v75
	v_fmac_f32_e32 v8, v4, v4
	v_fmac_f32_e32 v8, v5, v5
	v_lshlrev_b32_e32 v4, 16, v76
	v_and_b32_e32 v5, 0xffff0000, v76
	v_mul_f32_e32 v9, v4, v4
	v_fmac_f32_e32 v9, v5, v5
	v_lshlrev_b32_e32 v4, 16, v77
	v_and_b32_e32 v5, 0xffff0000, v77
	v_fmac_f32_e32 v9, v4, v4
	v_fmac_f32_e32 v9, v5, v5
	v_lshlrev_b32_e32 v4, 16, v78
	v_and_b32_e32 v5, 0xffff0000, v78
	v_fmac_f32_e32 v9, v4, v4
	v_fmac_f32_e32 v9, v5, v5
	v_lshlrev_b32_e32 v4, 16, v79
	v_and_b32_e32 v5, 0xffff0000, v79
	v_fmac_f32_e32 v9, v4, v4
	v_fmac_f32_e32 v9, v5, v5
	v_lshlrev_b32_e32 v4, 16, v80
	v_and_b32_e32 v5, 0xffff0000, v80
	v_mul_f32_e32 v10, v4, v4
	v_fmac_f32_e32 v10, v5, v5
	v_lshlrev_b32_e32 v4, 16, v81
	v_and_b32_e32 v5, 0xffff0000, v81
	v_fmac_f32_e32 v10, v4, v4
	v_fmac_f32_e32 v10, v5, v5
	v_lshlrev_b32_e32 v4, 16, v82
	v_and_b32_e32 v5, 0xffff0000, v82
	v_fmac_f32_e32 v10, v4, v4
	v_fmac_f32_e32 v10, v5, v5
	v_lshlrev_b32_e32 v4, 16, v83
	v_and_b32_e32 v5, 0xffff0000, v83
	v_fmac_f32_e32 v10, v4, v4
	v_fmac_f32_e32 v10, v5, v5
	v_lshlrev_b32_e32 v4, 16, v84
	v_and_b32_e32 v5, 0xffff0000, v84
	v_mul_f32_e32 v11, v4, v4
	v_fmac_f32_e32 v11, v5, v5
	v_lshlrev_b32_e32 v4, 16, v85
	v_and_b32_e32 v5, 0xffff0000, v85
	v_fmac_f32_e32 v11, v4, v4
	v_fmac_f32_e32 v11, v5, v5
	v_lshlrev_b32_e32 v4, 16, v86
	v_and_b32_e32 v5, 0xffff0000, v86
	v_fmac_f32_e32 v11, v4, v4
	v_fmac_f32_e32 v11, v5, v5
	v_lshlrev_b32_e32 v4, 16, v87
	v_and_b32_e32 v5, 0xffff0000, v87
	v_fmac_f32_e32 v11, v4, v4
	v_fmac_f32_e32 v11, v5, v5
	v_lshlrev_b32_e32 v4, 16, v88
	v_and_b32_e32 v5, 0xffff0000, v88
	v_mul_f32_e32 v12, v4, v4
	v_fmac_f32_e32 v12, v5, v5
	v_lshlrev_b32_e32 v4, 16, v89
	v_and_b32_e32 v5, 0xffff0000, v89
	v_fmac_f32_e32 v12, v4, v4
	v_fmac_f32_e32 v12, v5, v5
	v_lshlrev_b32_e32 v4, 16, v90
	v_and_b32_e32 v5, 0xffff0000, v90
	v_fmac_f32_e32 v12, v4, v4
	v_fmac_f32_e32 v12, v5, v5
	v_lshlrev_b32_e32 v4, 16, v91
	v_and_b32_e32 v5, 0xffff0000, v91
	v_fmac_f32_e32 v12, v4, v4
	v_fmac_f32_e32 v12, v5, v5
	v_lshlrev_b32_e32 v4, 16, v92
	v_and_b32_e32 v5, 0xffff0000, v92
	v_mul_f32_e32 v13, v4, v4
	v_fmac_f32_e32 v13, v5, v5
	v_lshlrev_b32_e32 v4, 16, v93
	v_and_b32_e32 v5, 0xffff0000, v93
	v_fmac_f32_e32 v13, v4, v4
	v_fmac_f32_e32 v13, v5, v5
	v_lshlrev_b32_e32 v4, 16, v94
	v_and_b32_e32 v5, 0xffff0000, v94
	v_fmac_f32_e32 v13, v4, v4
	v_fmac_f32_e32 v13, v5, v5
	v_lshlrev_b32_e32 v4, 16, v95
	v_and_b32_e32 v5, 0xffff0000, v95
	v_fmac_f32_e32 v13, v4, v4
	v_fmac_f32_e32 v13, v5, v5
	v_lshlrev_b32_e32 v4, 16, v96
	v_and_b32_e32 v5, 0xffff0000, v96
	v_mul_f32_e32 v14, v4, v4
	v_fmac_f32_e32 v14, v5, v5
	v_lshlrev_b32_e32 v4, 16, v97
	v_and_b32_e32 v5, 0xffff0000, v97
	v_fmac_f32_e32 v14, v4, v4
	v_fmac_f32_e32 v14, v5, v5
	v_lshlrev_b32_e32 v4, 16, v98
	v_and_b32_e32 v5, 0xffff0000, v98
	v_fmac_f32_e32 v14, v4, v4
	v_fmac_f32_e32 v14, v5, v5
	v_lshlrev_b32_e32 v4, 16, v99
	v_and_b32_e32 v5, 0xffff0000, v99
	v_fmac_f32_e32 v14, v4, v4
	v_fmac_f32_e32 v14, v5, v5
	v_lshlrev_b32_e32 v4, 16, v100
	v_and_b32_e32 v5, 0xffff0000, v100
	v_mul_f32_e32 v15, v4, v4
	v_fmac_f32_e32 v15, v5, v5
	v_lshlrev_b32_e32 v4, 16, v101
	v_and_b32_e32 v5, 0xffff0000, v101
	v_fmac_f32_e32 v15, v4, v4
	v_fmac_f32_e32 v15, v5, v5
	v_lshlrev_b32_e32 v4, 16, v102
	v_and_b32_e32 v5, 0xffff0000, v102
	v_fmac_f32_e32 v15, v4, v4
	v_fmac_f32_e32 v15, v5, v5
	v_lshlrev_b32_e32 v4, 16, v103
	v_and_b32_e32 v5, 0xffff0000, v103
	v_fmac_f32_e32 v15, v4, v4
	v_fmac_f32_e32 v15, v5, v5
	v_add_f32_dpp v8, v8, v8 quad_perm:[1,0,3,2] row_mask:0xf bank_mask:0xf
	v_add_f32_dpp v9, v9, v9 quad_perm:[1,0,3,2] row_mask:0xf bank_mask:0xf
	v_add_f32_dpp v10, v10, v10 quad_perm:[1,0,3,2] row_mask:0xf bank_mask:0xf
	v_add_f32_dpp v11, v11, v11 quad_perm:[1,0,3,2] row_mask:0xf bank_mask:0xf
	v_add_f32_dpp v12, v12, v12 quad_perm:[1,0,3,2] row_mask:0xf bank_mask:0xf
	v_add_f32_dpp v13, v13, v13 quad_perm:[1,0,3,2] row_mask:0xf bank_mask:0xf
	v_add_f32_dpp v14, v14, v14 quad_perm:[1,0,3,2] row_mask:0xf bank_mask:0xf
	v_add_f32_dpp v15, v15, v15 quad_perm:[1,0,3,2] row_mask:0xf bank_mask:0xf
	v_add_f32_dpp v8, v8, v8 quad_perm:[2,3,0,1] row_mask:0xf bank_mask:0xf
	v_add_f32_dpp v9, v9, v9 quad_perm:[2,3,0,1] row_mask:0xf bank_mask:0xf
	v_add_f32_dpp v10, v10, v10 quad_perm:[2,3,0,1] row_mask:0xf bank_mask:0xf
	v_add_f32_dpp v11, v11, v11 quad_perm:[2,3,0,1] row_mask:0xf bank_mask:0xf
	v_add_f32_dpp v12, v12, v12 quad_perm:[2,3,0,1] row_mask:0xf bank_mask:0xf
	v_add_f32_dpp v13, v13, v13 quad_perm:[2,3,0,1] row_mask:0xf bank_mask:0xf
	v_add_f32_dpp v14, v14, v14 quad_perm:[2,3,0,1] row_mask:0xf bank_mask:0xf
	v_add_f32_dpp v15, v15, v15 quad_perm:[2,3,0,1] row_mask:0xf bank_mask:0xf
	v_add_f32_dpp v8, v8, v8 row_half_mirror row_mask:0xf bank_mask:0xf
	v_add_f32_dpp v9, v9, v9 row_half_mirror row_mask:0xf bank_mask:0xf
	v_add_f32_dpp v10, v10, v10 row_half_mirror row_mask:0xf bank_mask:0xf
	v_add_f32_dpp v11, v11, v11 row_half_mirror row_mask:0xf bank_mask:0xf
	v_add_f32_dpp v12, v12, v12 row_half_mirror row_mask:0xf bank_mask:0xf
	v_add_f32_dpp v13, v13, v13 row_half_mirror row_mask:0xf bank_mask:0xf
	v_add_f32_dpp v14, v14, v14 row_half_mirror row_mask:0xf bank_mask:0xf
	v_add_f32_dpp v15, v15, v15 row_half_mirror row_mask:0xf bank_mask:0xf
; #define GAS __attribute__((address_space(1)))
; __device__ __forceinline__ v4u pack8(const float (&f)[8]) { v4u o; o.x = cvt_pk_bf16(f[0], f[1]); o.y = cvt_pk_bf16(f[2], f[3]); o.z = cvt_pk_bf16(f[4], f[5]); o.w = cvt_pk_bf16(f[6], f[7]); return o; }
; __device__ __forceinline__ float wave_sum(float v) {
; #pragma unroll
;     for (int o = 1; o < 64; o <<= 1) v += __shfl_xor(v, o);
;     return v;
; }
; __device__ __forceinline__ void phase_gnorm(const Params& P, int seg) {
;     ...
;             s = wave_sum(s); const float rs = rsqrtf(s * (1.f / 512.f) + EPS);
; #pragma unroll
;             for (int e = 0; e < 8; ++e) f[e] *= rs;
;             *(GAS v4u*)(p + g * 512) = pack8(f); } }
	v_add_f32_dpp v8, v8, v8 row_mirror row_mask:0xf bank_mask:0xf
	v_add_f32_dpp v9, v9, v9 row_mirror row_mask:0xf bank_mask:0xf
	v_add_f32_dpp v10, v10, v10 row_mirror row_mask:0xf bank_mask:0xf
	v_add_f32_dpp v11, v11, v11 row_mirror row_mask:0xf bank_mask:0xf
	v_add_f32_dpp v12, v12, v12 row_mirror row_mask:0xf bank_mask:0xf
	v_add_f32_dpp v13, v13, v13 row_mirror row_mask:0xf bank_mask:0xf
	v_add_f32_dpp v14, v14, v14 row_mirror row_mask:0xf bank_mask:0xf
	v_add_f32_dpp v15, v15, v15 row_mirror row_mask:0xf bank_mask:0xf
	v_add_f32_dpp v8, v8, v8 row_bcast:15 row_mask:0xa bank_mask:0xf
	v_add_f32_dpp v9, v9, v9 row_bcast:15 row_mask:0xa bank_mask:0xf
	v_add_f32_dpp v10, v10, v10 row_bcast:15 row_mask:0xa bank_mask:0xf
	v_add_f32_dpp v11, v11, v11 row_bcast:15 row_mask:0xa bank_mask:0xf
	v_add_f32_dpp v12, v12, v12 row_bcast:15 row_mask:0xa bank_mask:0xf
	v_add_f32_dpp v13, v13, v13 row_bcast:15 row_mask:0xa bank_mask:0xf
	v_add_f32_dpp v14, v14, v14 row_bcast:15 row_mask:0xa bank_mask:0xf
	v_add_f32_dpp v15, v15, v15 row_bcast:15 row_mask:0xa bank_mask:0xf
	v_add_f32_dpp v8, v8, v8 row_bcast:31 row_mask:0xc bank_mask:0xf
	v_add_f32_dpp v9, v9, v9 row_bcast:31 row_mask:0xc bank_mask:0xf
	v_add_f32_dpp v10, v10, v10 row_bcast:31 row_mask:0xc bank_mask:0xf
	v_add_f32_dpp v11, v11, v11 row_bcast:31 row_mask:0xc bank_mask:0xf
	v_add_f32_dpp v12, v12, v12 row_bcast:31 row_mask:0xc bank_mask:0xf
	v_add_f32_dpp v13, v13, v13 row_bcast:31 row_mask:0xc bank_mask:0xf
	v_add_f32_dpp v14, v14, v14 row_bcast:31 row_mask:0xc bank_mask:0xf
	v_add_f32_dpp v15, v15, v15 row_bcast:31 row_mask:0xc bank_mask:0xf
	s_nop 1
	v_readlane_b32 s68, v8, 63
	v_readlane_b32 s69, v9, 63
	v_readlane_b32 s70, v10, 63
	v_readlane_b32 s71, v11, 63
	v_readlane_b32 s72, v12, 63
	v_readlane_b32 s73, v13, 63
	v_readlane_b32 s74, v14, 63
	v_readlane_b32 s75, v15, 63
	s_nop 1
	v_mov_b32_e32 v16, s68
	v_mov_b32_e32 v17, s69
	v_mov_b32_e32 v18, s70
	v_mov_b32_e32 v19, s71
	v_mov_b32_e32 v20, s72
	v_mov_b32_e32 v21, s73
	v_mov_b32_e32 v22, s74
	v_mov_b32_e32 v23, s75
	v_fmamk_f32 v16, v16, 0x3b000000, v176
	v_fmamk_f32 v17, v17, 0x3b000000, v176
	v_fmamk_f32 v18, v18, 0x3b000000, v176
	v_fmamk_f32 v19, v19, 0x3b000000, v176
	v_fmamk_f32 v20, v20, 0x3b000000, v176
	v_fmamk_f32 v21, v21, 0x3b000000, v176
	v_fmamk_f32 v22, v22, 0x3b000000, v176
	v_fmamk_f32 v23, v23, 0x3b000000, v176
	v_rsq_f32_e32 v16, v16
	v_rsq_f32_e32 v17, v17
	v_rsq_f32_e32 v18, v18
	v_rsq_f32_e32 v19, v19
	v_rsq_f32_e32 v20, v20
	v_rsq_f32_e32 v21, v21
	v_rsq_f32_e32 v22, v22
	v_rsq_f32_e32 v23, v23
	v_lshlrev_b32_e32 v4, 16, v72
	v_and_b32_e32 v5, 0xffff0000, v72
	v_mul_f32_e32 v4, v16, v4
	v_mul_f32_e32 v5, v16, v5
	v_cvt_pk_bf16_f32 v72, v4, v5
	v_lshlrev_b32_e32 v4, 16, v73
	v_and_b32_e32 v5, 0xffff0000, v73
	v_mul_f32_e32 v4, v16, v4
	v_mul_f32_e32 v5, v16, v5
	v_cvt_pk_bf16_f32 v73, v4, v5
	v_lshlrev_b32_e32 v4, 16, v74
	v_and_b32_e32 v5, 0xffff0000, v74
	v_mul_f32_e32 v4, v16, v4
	v_mul_f32_e32 v5, v16, v5
	v_cvt_pk_bf16_f32 v74, v4, v5
	v_lshlrev_b32_e32 v4, 16, v75
	v_and_b32_e32 v5, 0xffff0000, v75
	v_mul_f32_e32 v4, v16, v4
	v_mul_f32_e32 v5, v16, v5
	v_cvt_pk_bf16_f32 v75, v4, v5
	global_store_dwordx4 v24, v[72:75], s[56:57]
	v_lshlrev_b32_e32 v4, 16, v76
	v_and_b32_e32 v5, 0xffff0000, v76
	v_mul_f32_e32 v4, v17, v4
	v_mul_f32_e32 v5, v17, v5
	v_cvt_pk_bf16_f32 v76, v4, v5
	v_lshlrev_b32_e32 v4, 16, v77
	v_and_b32_e32 v5, 0xffff0000, v77
	v_mul_f32_e32 v4, v17, v4
	v_mul_f32_e32 v5, v17, v5
	v_cvt_pk_bf16_f32 v77, v4, v5
	v_lshlrev_b32_e32 v4, 16, v78
	v_and_b32_e32 v5, 0xffff0000, v78
	v_mul_f32_e32 v4, v17, v4
	v_mul_f32_e32 v5, v17, v5
	v_cvt_pk_bf16_f32 v78, v4, v5
	v_lshlrev_b32_e32 v4, 16, v79
	v_and_b32_e32 v5, 0xffff0000, v79
	v_mul_f32_e32 v4, v17, v4
	v_mul_f32_e32 v5, v17, v5
	v_cvt_pk_bf16_f32 v79, v4, v5
	global_store_dwordx4 v24, v[76:79], s[56:57] offset:1024
	v_lshlrev_b32_e32 v4, 16, v80
	v_and_b32_e32 v5, 0xffff0000, v80
	v_mul_f32_e32 v4, v18, v4
	v_mul_f32_e32 v5, v18, v5
	v_cvt_pk_bf16_f32 v80, v4, v5
	v_lshlrev_b32_e32 v4, 16, v81
	v_and_b32_e32 v5, 0xffff0000, v81
	v_mul_f32_e32 v4, v18, v4
	v_mul_f32_e32 v5, v18, v5
	v_cvt_pk_bf16_f32 v81, v4, v5
	v_lshlrev_b32_e32 v4, 16, v82
	v_and_b32_e32 v5, 0xffff0000, v82
	v_mul_f32_e32 v4, v18, v4
	v_mul_f32_e32 v5, v18, v5
	v_cvt_pk_bf16_f32 v82, v4, v5
	v_lshlrev_b32_e32 v4, 16, v83
	v_and_b32_e32 v5, 0xffff0000, v83
	v_mul_f32_e32 v4, v18, v4
	v_mul_f32_e32 v5, v18, v5
	v_cvt_pk_bf16_f32 v83, v4, v5
	global_store_dwordx4 v24, v[80:83], s[56:57] offset:2048
	v_lshlrev_b32_e32 v4, 16, v84
	v_and_b32_e32 v5, 0xffff0000, v84
	v_mul_f32_e32 v4, v19, v4
	v_mul_f32_e32 v5, v19, v5
	v_cvt_pk_bf16_f32 v84, v4, v5
	v_lshlrev_b32_e32 v4, 16, v85
	v_and_b32_e32 v5, 0xffff0000, v85
	v_mul_f32_e32 v4, v19, v4
	v_mul_f32_e32 v5, v19, v5
	v_cvt_pk_bf16_f32 v85, v4, v5
	v_lshlrev_b32_e32 v4, 16, v86
	v_and_b32_e32 v5, 0xffff0000, v86
	v_mul_f32_e32 v4, v19, v4
	v_mul_f32_e32 v5, v19, v5
	v_cvt_pk_bf16_f32 v86, v4, v5
	v_lshlrev_b32_e32 v4, 16, v87
	v_and_b32_e32 v5, 0xffff0000, v87
	v_mul_f32_e32 v4, v19, v4
	v_mul_f32_e32 v5, v19, v5
	v_cvt_pk_bf16_f32 v87, v4, v5
	global_store_dwordx4 v24, v[84:87], s[56:57] offset:3072
	v_lshlrev_b32_e32 v4, 16, v88
	v_and_b32_e32 v5, 0xffff0000, v88
	v_mul_f32_e32 v4, v20, v4
	v_mul_f32_e32 v5, v20, v5
	v_cvt_pk_bf16_f32 v88, v4, v5
	v_lshlrev_b32_e32 v4, 16, v89
	v_and_b32_e32 v5, 0xffff0000, v89
	v_mul_f32_e32 v4, v20, v4
	v_mul_f32_e32 v5, v20, v5
	v_cvt_pk_bf16_f32 v89, v4, v5
	v_lshlrev_b32_e32 v4, 16, v90
	v_and_b32_e32 v5, 0xffff0000, v90
	v_mul_f32_e32 v4, v20, v4
	v_mul_f32_e32 v5, v20, v5
; #define GAS __attribute__((address_space(1)))
; __device__ __forceinline__ void unpack8(const v4u v, float (&f)[8]) { f[0] = bflo(v.x); f[1] = bfhi(v.x); f[2] = bflo(v.y); f[3] = bfhi(v.y); f[4] = bflo(v.z); f[5] = bfhi(v.z); f[6] = bflo(v.w); f[7] = bfhi(v.w); }
; __device__ __forceinline__ v4u pack8(const float (&f)[8]) { v4u o; o.x = cvt_pk_bf16(f[0], f[1]); o.y = cvt_pk_bf16(f[2], f[3]); o.z = cvt_pk_bf16(f[4], f[5]); o.w = cvt_pk_bf16(f[6], f[7]); return o; }
; __device__ __forceinline__ void phase_gnorm(const Params& P, int seg) {
;     ...
;         for (int g = 0; g < 8; ++g) { float f[8]; unpack8(raw[g], f); float s = 0.f;
; #pragma unroll
;             for (int e = 0; e < 8; ++e) s += f[e] * f[e];
;     ...
; #pragma unroll
;             for (int e = 0; e < 8; ++e) f[e] *= rs;
;             *(GAS v4u*)(p + g * 512) = pack8(f); } }
	v_cvt_pk_bf16_f32 v90, v4, v5
	v_lshlrev_b32_e32 v4, 16, v91
	v_and_b32_e32 v5, 0xffff0000, v91
	v_mul_f32_e32 v4, v20, v4
	v_mul_f32_e32 v5, v20, v5
	v_cvt_pk_bf16_f32 v91, v4, v5
	global_store_dwordx4 v25, v[88:91], s[56:57]
	v_lshlrev_b32_e32 v4, 16, v92
	v_and_b32_e32 v5, 0xffff0000, v92
	v_mul_f32_e32 v4, v21, v4
	v_mul_f32_e32 v5, v21, v5
	v_cvt_pk_bf16_f32 v92, v4, v5
	v_lshlrev_b32_e32 v4, 16, v93
	v_and_b32_e32 v5, 0xffff0000, v93
	v_mul_f32_e32 v4, v21, v4
	v_mul_f32_e32 v5, v21, v5
	v_cvt_pk_bf16_f32 v93, v4, v5
	v_lshlrev_b32_e32 v4, 16, v94
	v_and_b32_e32 v5, 0xffff0000, v94
	v_mul_f32_e32 v4, v21, v4
	v_mul_f32_e32 v5, v21, v5
	v_cvt_pk_bf16_f32 v94, v4, v5
	v_lshlrev_b32_e32 v4, 16, v95
	v_and_b32_e32 v5, 0xffff0000, v95
	v_mul_f32_e32 v4, v21, v4
	v_mul_f32_e32 v5, v21, v5
	v_cvt_pk_bf16_f32 v95, v4, v5
	global_store_dwordx4 v25, v[92:95], s[56:57] offset:1024
	v_lshlrev_b32_e32 v4, 16, v96
	v_and_b32_e32 v5, 0xffff0000, v96
	v_mul_f32_e32 v4, v22, v4
	v_mul_f32_e32 v5, v22, v5
	v_cvt_pk_bf16_f32 v96, v4, v5
	v_lshlrev_b32_e32 v4, 16, v97
	v_and_b32_e32 v5, 0xffff0000, v97
	v_mul_f32_e32 v4, v22, v4
	v_mul_f32_e32 v5, v22, v5
	v_cvt_pk_bf16_f32 v97, v4, v5
	v_lshlrev_b32_e32 v4, 16, v98
	v_and_b32_e32 v5, 0xffff0000, v98
	v_mul_f32_e32 v4, v22, v4
	v_mul_f32_e32 v5, v22, v5
	v_cvt_pk_bf16_f32 v98, v4, v5
	v_lshlrev_b32_e32 v4, 16, v99
	v_and_b32_e32 v5, 0xffff0000, v99
	v_mul_f32_e32 v4, v22, v4
	v_mul_f32_e32 v5, v22, v5
	v_cvt_pk_bf16_f32 v99, v4, v5
	global_store_dwordx4 v25, v[96:99], s[56:57] offset:2048
	v_lshlrev_b32_e32 v4, 16, v100
	v_and_b32_e32 v5, 0xffff0000, v100
	v_mul_f32_e32 v4, v23, v4
	v_mul_f32_e32 v5, v23, v5
	v_cvt_pk_bf16_f32 v100, v4, v5
	v_lshlrev_b32_e32 v4, 16, v101
	v_and_b32_e32 v5, 0xffff0000, v101
	v_mul_f32_e32 v4, v23, v4
	v_mul_f32_e32 v5, v23, v5
	v_cvt_pk_bf16_f32 v101, v4, v5
	v_lshlrev_b32_e32 v4, 16, v102
	v_and_b32_e32 v5, 0xffff0000, v102
	v_mul_f32_e32 v4, v23, v4
	v_mul_f32_e32 v5, v23, v5
	v_cvt_pk_bf16_f32 v102, v4, v5
	v_lshlrev_b32_e32 v4, 16, v103
	v_and_b32_e32 v5, 0xffff0000, v103
	v_mul_f32_e32 v4, v23, v4
	v_mul_f32_e32 v5, v23, v5
	v_cvt_pk_bf16_f32 v103, v4, v5
	global_store_dwordx4 v25, v[100:103], s[56:57] offset:3072
	s_waitcnt vmcnt(24)
	v_lshlrev_b32_e32 v4, 16, v120
	v_and_b32_e32 v5, 0xffff0000, v120
	v_mul_f32_e32 v8, v4, v4
	v_fmac_f32_e32 v8, v5, v5
	v_lshlrev_b32_e32 v4, 16, v121
	v_and_b32_e32 v5, 0xffff0000, v121
	v_fmac_f32_e32 v8, v4, v4
	v_fmac_f32_e32 v8, v5, v5
	v_lshlrev_b32_e32 v4, 16, v122
	v_and_b32_e32 v5, 0xffff0000, v122
	v_fmac_f32_e32 v8, v4, v4
	v_fmac_f32_e32 v8, v5, v5
	v_lshlrev_b32_e32 v4, 16, v123
	v_and_b32_e32 v5, 0xffff0000, v123
	v_fmac_f32_e32 v8, v4, v4
	v_fmac_f32_e32 v8, v5, v5
	v_lshlrev_b32_e32 v4, 16, v124
	v_and_b32_e32 v5, 0xffff0000, v124
	v_mul_f32_e32 v9, v4, v4
	v_fmac_f32_e32 v9, v5, v5
	v_lshlrev_b32_e32 v4, 16, v125
	v_and_b32_e32 v5, 0xffff0000, v125
	v_fmac_f32_e32 v9, v4, v4
	v_fmac_f32_e32 v9, v5, v5
	v_lshlrev_b32_e32 v4, 16, v126
	v_and_b32_e32 v5, 0xffff0000, v126
	v_fmac_f32_e32 v9, v4, v4
	v_fmac_f32_e32 v9, v5, v5
	v_lshlrev_b32_e32 v4, 16, v127
	v_and_b32_e32 v5, 0xffff0000, v127
	v_fmac_f32_e32 v9, v4, v4
	v_fmac_f32_e32 v9, v5, v5
	v_lshlrev_b32_e32 v4, 16, v128
	v_and_b32_e32 v5, 0xffff0000, v128
	v_mul_f32_e32 v10, v4, v4
	v_fmac_f32_e32 v10, v5, v5
	v_lshlrev_b32_e32 v4, 16, v129
	v_and_b32_e32 v5, 0xffff0000, v129
	v_fmac_f32_e32 v10, v4, v4
	v_fmac_f32_e32 v10, v5, v5
	v_lshlrev_b32_e32 v4, 16, v130
	v_and_b32_e32 v5, 0xffff0000, v130
	v_fmac_f32_e32 v10, v4, v4
	v_fmac_f32_e32 v10, v5, v5
	v_lshlrev_b32_e32 v4, 16, v131
	v_and_b32_e32 v5, 0xffff0000, v131
	v_fmac_f32_e32 v10, v4, v4
	v_fmac_f32_e32 v10, v5, v5
	v_lshlrev_b32_e32 v4, 16, v132
	v_and_b32_e32 v5, 0xffff0000, v132
	v_mul_f32_e32 v11, v4, v4
	v_fmac_f32_e32 v11, v5, v5
	v_lshlrev_b32_e32 v4, 16, v133
	v_and_b32_e32 v5, 0xffff0000, v133
	v_fmac_f32_e32 v11, v4, v4
	v_fmac_f32_e32 v11, v5, v5
	v_lshlrev_b32_e32 v4, 16, v134
	v_and_b32_e32 v5, 0xffff0000, v134
	v_fmac_f32_e32 v11, v4, v4
	v_fmac_f32_e32 v11, v5, v5
	v_lshlrev_b32_e32 v4, 16, v135
	v_and_b32_e32 v5, 0xffff0000, v135
	v_fmac_f32_e32 v11, v4, v4
	v_fmac_f32_e32 v11, v5, v5
	v_lshlrev_b32_e32 v4, 16, v136
	v_and_b32_e32 v5, 0xffff0000, v136
	v_mul_f32_e32 v12, v4, v4
	v_fmac_f32_e32 v12, v5, v5
	v_lshlrev_b32_e32 v4, 16, v137
	v_and_b32_e32 v5, 0xffff0000, v137
	v_fmac_f32_e32 v12, v4, v4
	v_fmac_f32_e32 v12, v5, v5
	v_lshlrev_b32_e32 v4, 16, v138
	v_and_b32_e32 v5, 0xffff0000, v138
	v_fmac_f32_e32 v12, v4, v4
	v_fmac_f32_e32 v12, v5, v5
	v_lshlrev_b32_e32 v4, 16, v139
	v_and_b32_e32 v5, 0xffff0000, v139
	v_fmac_f32_e32 v12, v4, v4
	v_fmac_f32_e32 v12, v5, v5
	v_lshlrev_b32_e32 v4, 16, v140
	v_and_b32_e32 v5, 0xffff0000, v140
	v_mul_f32_e32 v13, v4, v4
	v_fmac_f32_e32 v13, v5, v5
	v_lshlrev_b32_e32 v4, 16, v141
	v_and_b32_e32 v5, 0xffff0000, v141
	v_fmac_f32_e32 v13, v4, v4
	v_fmac_f32_e32 v13, v5, v5
	v_lshlrev_b32_e32 v4, 16, v142
	v_and_b32_e32 v5, 0xffff0000, v142
	v_fmac_f32_e32 v13, v4, v4
	v_fmac_f32_e32 v13, v5, v5
	v_lshlrev_b32_e32 v4, 16, v143
	v_and_b32_e32 v5, 0xffff0000, v143
	v_fmac_f32_e32 v13, v4, v4
	v_fmac_f32_e32 v13, v5, v5
	v_lshlrev_b32_e32 v4, 16, v144
	v_and_b32_e32 v5, 0xffff0000, v144
	v_mul_f32_e32 v14, v4, v4
	v_fmac_f32_e32 v14, v5, v5
	v_lshlrev_b32_e32 v4, 16, v145
	v_and_b32_e32 v5, 0xffff0000, v145
	v_fmac_f32_e32 v14, v4, v4
	v_fmac_f32_e32 v14, v5, v5
	v_lshlrev_b32_e32 v4, 16, v146
	v_and_b32_e32 v5, 0xffff0000, v146
	v_fmac_f32_e32 v14, v4, v4
	v_fmac_f32_e32 v14, v5, v5
	v_lshlrev_b32_e32 v4, 16, v147
	v_and_b32_e32 v5, 0xffff0000, v147
; #define GAS __attribute__((address_space(1)))
; __device__ __forceinline__ void unpack8(const v4u v, float (&f)[8]) { f[0] = bflo(v.x); f[1] = bfhi(v.x); f[2] = bflo(v.y); f[3] = bfhi(v.y); f[4] = bflo(v.z); f[5] = bfhi(v.z); f[6] = bflo(v.w); f[7] = bfhi(v.w); }
; __device__ __forceinline__ v4u pack8(const float (&f)[8]) { v4u o; o.x = cvt_pk_bf16(f[0], f[1]); o.y = cvt_pk_bf16(f[2], f[3]); o.z = cvt_pk_bf16(f[4], f[5]); o.w = cvt_pk_bf16(f[6], f[7]); return o; }
; __device__ __forceinline__ void phase_gnorm(const Params& P, int seg) {
;     ...
;         for (int g = 0; g < 8; ++g) { float f[8]; unpack8(raw[g], f); float s = 0.f;
; #pragma unroll
;             for (int e = 0; e < 8; ++e) s += f[e] * f[e];
;             s = wave_sum(s); const float rs = rsqrtf(s * (1.f / 512.f) + EPS);
; #pragma unroll
;             for (int e = 0; e < 8; ++e) f[e] *= rs;
;             *(GAS v4u*)(p + g * 512) = pack8(f); } }
	v_fmac_f32_e32 v14, v4, v4
	v_fmac_f32_e32 v14, v5, v5
	v_lshlrev_b32_e32 v4, 16, v148
	v_and_b32_e32 v5, 0xffff0000, v148
	v_mul_f32_e32 v15, v4, v4
	v_fmac_f32_e32 v15, v5, v5
	v_lshlrev_b32_e32 v4, 16, v149
	v_and_b32_e32 v5, 0xffff0000, v149
	v_fmac_f32_e32 v15, v4, v4
	v_fmac_f32_e32 v15, v5, v5
	v_lshlrev_b32_e32 v4, 16, v150
	v_and_b32_e32 v5, 0xffff0000, v150
	v_fmac_f32_e32 v15, v4, v4
	v_fmac_f32_e32 v15, v5, v5
	v_lshlrev_b32_e32 v4, 16, v151
	v_and_b32_e32 v5, 0xffff0000, v151
	v_fmac_f32_e32 v15, v4, v4
	v_fmac_f32_e32 v15, v5, v5
	v_add_f32_dpp v8, v8, v8 quad_perm:[1,0,3,2] row_mask:0xf bank_mask:0xf
	v_add_f32_dpp v9, v9, v9 quad_perm:[1,0,3,2] row_mask:0xf bank_mask:0xf
	v_add_f32_dpp v10, v10, v10 quad_perm:[1,0,3,2] row_mask:0xf bank_mask:0xf
	v_add_f32_dpp v11, v11, v11 quad_perm:[1,0,3,2] row_mask:0xf bank_mask:0xf
	v_add_f32_dpp v12, v12, v12 quad_perm:[1,0,3,2] row_mask:0xf bank_mask:0xf
	v_add_f32_dpp v13, v13, v13 quad_perm:[1,0,3,2] row_mask:0xf bank_mask:0xf
	v_add_f32_dpp v14, v14, v14 quad_perm:[1,0,3,2] row_mask:0xf bank_mask:0xf
	v_add_f32_dpp v15, v15, v15 quad_perm:[1,0,3,2] row_mask:0xf bank_mask:0xf
	v_add_f32_dpp v8, v8, v8 quad_perm:[2,3,0,1] row_mask:0xf bank_mask:0xf
	v_add_f32_dpp v9, v9, v9 quad_perm:[2,3,0,1] row_mask:0xf bank_mask:0xf
	v_add_f32_dpp v10, v10, v10 quad_perm:[2,3,0,1] row_mask:0xf bank_mask:0xf
	v_add_f32_dpp v11, v11, v11 quad_perm:[2,3,0,1] row_mask:0xf bank_mask:0xf
	v_add_f32_dpp v12, v12, v12 quad_perm:[2,3,0,1] row_mask:0xf bank_mask:0xf
	v_add_f32_dpp v13, v13, v13 quad_perm:[2,3,0,1] row_mask:0xf bank_mask:0xf
	v_add_f32_dpp v14, v14, v14 quad_perm:[2,3,0,1] row_mask:0xf bank_mask:0xf
	v_add_f32_dpp v15, v15, v15 quad_perm:[2,3,0,1] row_mask:0xf bank_mask:0xf
	v_add_f32_dpp v8, v8, v8 row_half_mirror row_mask:0xf bank_mask:0xf
	v_add_f32_dpp v9, v9, v9 row_half_mirror row_mask:0xf bank_mask:0xf
	v_add_f32_dpp v10, v10, v10 row_half_mirror row_mask:0xf bank_mask:0xf
	v_add_f32_dpp v11, v11, v11 row_half_mirror row_mask:0xf bank_mask:0xf
	v_add_f32_dpp v12, v12, v12 row_half_mirror row_mask:0xf bank_mask:0xf
	v_add_f32_dpp v13, v13, v13 row_half_mirror row_mask:0xf bank_mask:0xf
	v_add_f32_dpp v14, v14, v14 row_half_mirror row_mask:0xf bank_mask:0xf
	v_add_f32_dpp v15, v15, v15 row_half_mirror row_mask:0xf bank_mask:0xf
	v_add_f32_dpp v8, v8, v8 row_mirror row_mask:0xf bank_mask:0xf
	v_add_f32_dpp v9, v9, v9 row_mirror row_mask:0xf bank_mask:0xf
	v_add_f32_dpp v10, v10, v10 row_mirror row_mask:0xf bank_mask:0xf
	v_add_f32_dpp v11, v11, v11 row_mirror row_mask:0xf bank_mask:0xf
	v_add_f32_dpp v12, v12, v12 row_mirror row_mask:0xf bank_mask:0xf
	v_add_f32_dpp v13, v13, v13 row_mirror row_mask:0xf bank_mask:0xf
	v_add_f32_dpp v14, v14, v14 row_mirror row_mask:0xf bank_mask:0xf
	v_add_f32_dpp v15, v15, v15 row_mirror row_mask:0xf bank_mask:0xf
	v_add_f32_dpp v8, v8, v8 row_bcast:15 row_mask:0xa bank_mask:0xf
	v_add_f32_dpp v9, v9, v9 row_bcast:15 row_mask:0xa bank_mask:0xf
	v_add_f32_dpp v10, v10, v10 row_bcast:15 row_mask:0xa bank_mask:0xf
	v_add_f32_dpp v11, v11, v11 row_bcast:15 row_mask:0xa bank_mask:0xf
	v_add_f32_dpp v12, v12, v12 row_bcast:15 row_mask:0xa bank_mask:0xf
	v_add_f32_dpp v13, v13, v13 row_bcast:15 row_mask:0xa bank_mask:0xf
	v_add_f32_dpp v14, v14, v14 row_bcast:15 row_mask:0xa bank_mask:0xf
	v_add_f32_dpp v15, v15, v15 row_bcast:15 row_mask:0xa bank_mask:0xf
	v_add_f32_dpp v8, v8, v8 row_bcast:31 row_mask:0xc bank_mask:0xf
	v_add_f32_dpp v9, v9, v9 row_bcast:31 row_mask:0xc bank_mask:0xf
	v_add_f32_dpp v10, v10, v10 row_bcast:31 row_mask:0xc bank_mask:0xf
	v_add_f32_dpp v11, v11, v11 row_bcast:31 row_mask:0xc bank_mask:0xf
	v_add_f32_dpp v12, v12, v12 row_bcast:31 row_mask:0xc bank_mask:0xf
	v_add_f32_dpp v13, v13, v13 row_bcast:31 row_mask:0xc bank_mask:0xf
	v_add_f32_dpp v14, v14, v14 row_bcast:31 row_mask:0xc bank_mask:0xf
	v_add_f32_dpp v15, v15, v15 row_bcast:31 row_mask:0xc bank_mask:0xf
	s_nop 1
	v_readlane_b32 s68, v8, 63
	v_readlane_b32 s69, v9, 63
	v_readlane_b32 s70, v10, 63
	v_readlane_b32 s71, v11, 63
	v_readlane_b32 s72, v12, 63
	v_readlane_b32 s73, v13, 63
	v_readlane_b32 s74, v14, 63
	v_readlane_b32 s75, v15, 63
	s_nop 1
	v_mov_b32_e32 v16, s68
	v_mov_b32_e32 v17, s69
	v_mov_b32_e32 v18, s70
	v_mov_b32_e32 v19, s71
	v_mov_b32_e32 v20, s72
	v_mov_b32_e32 v21, s73
	v_mov_b32_e32 v22, s74
	v_mov_b32_e32 v23, s75
	v_fmamk_f32 v16, v16, 0x3b000000, v176
	v_fmamk_f32 v17, v17, 0x3b000000, v176
	v_fmamk_f32 v18, v18, 0x3b000000, v176
	v_fmamk_f32 v19, v19, 0x3b000000, v176
	v_fmamk_f32 v20, v20, 0x3b000000, v176
	v_fmamk_f32 v21, v21, 0x3b000000, v176
	v_fmamk_f32 v22, v22, 0x3b000000, v176
	v_fmamk_f32 v23, v23, 0x3b000000, v176
	v_rsq_f32_e32 v16, v16
	v_rsq_f32_e32 v17, v17
	v_rsq_f32_e32 v18, v18
	v_rsq_f32_e32 v19, v19
	v_rsq_f32_e32 v20, v20
	v_rsq_f32_e32 v21, v21
	v_rsq_f32_e32 v22, v22
	v_rsq_f32_e32 v23, v23
	v_lshlrev_b32_e32 v4, 16, v120
	v_and_b32_e32 v5, 0xffff0000, v120
	v_mul_f32_e32 v4, v16, v4
	v_mul_f32_e32 v5, v16, v5
	v_cvt_pk_bf16_f32 v120, v4, v5
	v_lshlrev_b32_e32 v4, 16, v121
	v_and_b32_e32 v5, 0xffff0000, v121
	v_mul_f32_e32 v4, v16, v4
	v_mul_f32_e32 v5, v16, v5
	v_cvt_pk_bf16_f32 v121, v4, v5
	v_lshlrev_b32_e32 v4, 16, v122
	v_and_b32_e32 v5, 0xffff0000, v122
	v_mul_f32_e32 v4, v16, v4
	v_mul_f32_e32 v5, v16, v5
	v_cvt_pk_bf16_f32 v122, v4, v5
	v_lshlrev_b32_e32 v4, 16, v123
	v_and_b32_e32 v5, 0xffff0000, v123
	v_mul_f32_e32 v4, v16, v4
	v_mul_f32_e32 v5, v16, v5
	v_cvt_pk_bf16_f32 v123, v4, v5
	global_store_dwordx4 v24, v[120:123], s[60:61]
	v_lshlrev_b32_e32 v4, 16, v124
	v_and_b32_e32 v5, 0xffff0000, v124
; #define GAS __attribute__((address_space(1)))
; __device__ __forceinline__ v4u pack8(const float (&f)[8]) { v4u o; o.x = cvt_pk_bf16(f[0], f[1]); o.y = cvt_pk_bf16(f[2], f[3]); o.z = cvt_pk_bf16(f[4], f[5]); o.w = cvt_pk_bf16(f[6], f[7]); return o; }
; __device__ __forceinline__ void phase_gnorm(const Params& P, int seg) {
;     ...
; #pragma unroll
;             for (int e = 0; e < 8; ++e) f[e] *= rs;
;             *(GAS v4u*)(p + g * 512) = pack8(f); } }
	v_mul_f32_e32 v4, v17, v4
	v_mul_f32_e32 v5, v17, v5
	v_cvt_pk_bf16_f32 v124, v4, v5
	v_lshlrev_b32_e32 v4, 16, v125
	v_and_b32_e32 v5, 0xffff0000, v125
	v_mul_f32_e32 v4, v17, v4
	v_mul_f32_e32 v5, v17, v5
	v_cvt_pk_bf16_f32 v125, v4, v5
	v_lshlrev_b32_e32 v4, 16, v126
	v_and_b32_e32 v5, 0xffff0000, v126
	v_mul_f32_e32 v4, v17, v4
	v_mul_f32_e32 v5, v17, v5
	v_cvt_pk_bf16_f32 v126, v4, v5
	v_lshlrev_b32_e32 v4, 16, v127
	v_and_b32_e32 v5, 0xffff0000, v127
	v_mul_f32_e32 v4, v17, v4
	v_mul_f32_e32 v5, v17, v5
	v_cvt_pk_bf16_f32 v127, v4, v5
	global_store_dwordx4 v24, v[124:127], s[60:61] offset:1024
	v_lshlrev_b32_e32 v4, 16, v128
	v_and_b32_e32 v5, 0xffff0000, v128
	v_mul_f32_e32 v4, v18, v4
	v_mul_f32_e32 v5, v18, v5
	v_cvt_pk_bf16_f32 v128, v4, v5
	v_lshlrev_b32_e32 v4, 16, v129
	v_and_b32_e32 v5, 0xffff0000, v129
	v_mul_f32_e32 v4, v18, v4
	v_mul_f32_e32 v5, v18, v5
	v_cvt_pk_bf16_f32 v129, v4, v5
	v_lshlrev_b32_e32 v4, 16, v130
	v_and_b32_e32 v5, 0xffff0000, v130
	v_mul_f32_e32 v4, v18, v4
	v_mul_f32_e32 v5, v18, v5
	v_cvt_pk_bf16_f32 v130, v4, v5
	v_lshlrev_b32_e32 v4, 16, v131
	v_and_b32_e32 v5, 0xffff0000, v131
	v_mul_f32_e32 v4, v18, v4
	v_mul_f32_e32 v5, v18, v5
	v_cvt_pk_bf16_f32 v131, v4, v5
	global_store_dwordx4 v24, v[128:131], s[60:61] offset:2048
	v_lshlrev_b32_e32 v4, 16, v132
	v_and_b32_e32 v5, 0xffff0000, v132
	v_mul_f32_e32 v4, v19, v4
	v_mul_f32_e32 v5, v19, v5
	v_cvt_pk_bf16_f32 v132, v4, v5
	v_lshlrev_b32_e32 v4, 16, v133
	v_and_b32_e32 v5, 0xffff0000, v133
	v_mul_f32_e32 v4, v19, v4
	v_mul_f32_e32 v5, v19, v5
	v_cvt_pk_bf16_f32 v133, v4, v5
	v_lshlrev_b32_e32 v4, 16, v134
	v_and_b32_e32 v5, 0xffff0000, v134
	v_mul_f32_e32 v4, v19, v4
	v_mul_f32_e32 v5, v19, v5
	v_cvt_pk_bf16_f32 v134, v4, v5
	v_lshlrev_b32_e32 v4, 16, v135
	v_and_b32_e32 v5, 0xffff0000, v135
	v_mul_f32_e32 v4, v19, v4
	v_mul_f32_e32 v5, v19, v5
	v_cvt_pk_bf16_f32 v135, v4, v5
	global_store_dwordx4 v24, v[132:135], s[60:61] offset:3072
	v_lshlrev_b32_e32 v4, 16, v136
	v_and_b32_e32 v5, 0xffff0000, v136
	v_mul_f32_e32 v4, v20, v4
	v_mul_f32_e32 v5, v20, v5
	v_cvt_pk_bf16_f32 v136, v4, v5
	v_lshlrev_b32_e32 v4, 16, v137
	v_and_b32_e32 v5, 0xffff0000, v137
	v_mul_f32_e32 v4, v20, v4
	v_mul_f32_e32 v5, v20, v5
	v_cvt_pk_bf16_f32 v137, v4, v5
	v_lshlrev_b32_e32 v4, 16, v138
	v_and_b32_e32 v5, 0xffff0000, v138
	v_mul_f32_e32 v4, v20, v4
	v_mul_f32_e32 v5, v20, v5
	v_cvt_pk_bf16_f32 v138, v4, v5
	v_lshlrev_b32_e32 v4, 16, v139
	v_and_b32_e32 v5, 0xffff0000, v139
	v_mul_f32_e32 v4, v20, v4
	v_mul_f32_e32 v5, v20, v5
	v_cvt_pk_bf16_f32 v139, v4, v5
	global_store_dwordx4 v25, v[136:139], s[60:61]
	v_lshlrev_b32_e32 v4, 16, v140
	v_and_b32_e32 v5, 0xffff0000, v140
	v_mul_f32_e32 v4, v21, v4
	v_mul_f32_e32 v5, v21, v5
	v_cvt_pk_bf16_f32 v140, v4, v5
	v_lshlrev_b32_e32 v4, 16, v141
	v_and_b32_e32 v5, 0xffff0000, v141
	v_mul_f32_e32 v4, v21, v4
	v_mul_f32_e32 v5, v21, v5
	v_cvt_pk_bf16_f32 v141, v4, v5
	v_lshlrev_b32_e32 v4, 16, v142
	v_and_b32_e32 v5, 0xffff0000, v142
	v_mul_f32_e32 v4, v21, v4
	v_mul_f32_e32 v5, v21, v5
	v_cvt_pk_bf16_f32 v142, v4, v5
	v_lshlrev_b32_e32 v4, 16, v143
	v_and_b32_e32 v5, 0xffff0000, v143
	v_mul_f32_e32 v4, v21, v4
	v_mul_f32_e32 v5, v21, v5
	v_cvt_pk_bf16_f32 v143, v4, v5
	global_store_dwordx4 v25, v[140:143], s[60:61] offset:1024
	v_lshlrev_b32_e32 v4, 16, v144
	v_and_b32_e32 v5, 0xffff0000, v144
	v_mul_f32_e32 v4, v22, v4
	v_mul_f32_e32 v5, v22, v5
	v_cvt_pk_bf16_f32 v144, v4, v5
	v_lshlrev_b32_e32 v4, 16, v145
	v_and_b32_e32 v5, 0xffff0000, v145
	v_mul_f32_e32 v4, v22, v4
	v_mul_f32_e32 v5, v22, v5
	v_cvt_pk_bf16_f32 v145, v4, v5
	v_lshlrev_b32_e32 v4, 16, v146
	v_and_b32_e32 v5, 0xffff0000, v146
	v_mul_f32_e32 v4, v22, v4
	v_mul_f32_e32 v5, v22, v5
	v_cvt_pk_bf16_f32 v146, v4, v5
	v_lshlrev_b32_e32 v4, 16, v147
	v_and_b32_e32 v5, 0xffff0000, v147
	v_mul_f32_e32 v4, v22, v4
	v_mul_f32_e32 v5, v22, v5
	v_cvt_pk_bf16_f32 v147, v4, v5
	global_store_dwordx4 v25, v[144:147], s[60:61] offset:2048
	v_lshlrev_b32_e32 v4, 16, v148
	v_and_b32_e32 v5, 0xffff0000, v148
	v_mul_f32_e32 v4, v23, v4
	v_mul_f32_e32 v5, v23, v5
	v_cvt_pk_bf16_f32 v148, v4, v5
	v_lshlrev_b32_e32 v4, 16, v149
	v_and_b32_e32 v5, 0xffff0000, v149
	v_mul_f32_e32 v4, v23, v4
	v_mul_f32_e32 v5, v23, v5
	v_cvt_pk_bf16_f32 v149, v4, v5
	v_lshlrev_b32_e32 v4, 16, v150
	v_and_b32_e32 v5, 0xffff0000, v150
	v_mul_f32_e32 v4, v23, v4
	v_mul_f32_e32 v5, v23, v5
	v_cvt_pk_bf16_f32 v150, v4, v5
	v_lshlrev_b32_e32 v4, 16, v151
	v_and_b32_e32 v5, 0xffff0000, v151
	v_mul_f32_e32 v4, v23, v4
	v_mul_f32_e32 v5, v23, v5
	v_cvt_pk_bf16_f32 v151, v4, v5
	global_store_dwordx4 v25, v[148:151], s[60:61] offset:3072
	s_waitcnt vmcnt(24)
; __device__ __forceinline__ void unpack8(const v4u v, float (&f)[8]) { f[0] = bflo(v.x); f[1] = bfhi(v.x); f[2] = bflo(v.y); f[3] = bfhi(v.y); f[4] = bflo(v.z); f[5] = bfhi(v.z); f[6] = bflo(v.w); f[7] = bfhi(v.w); }
; __device__ __forceinline__ void phase_gnorm(const Params& P, int seg) {
;     ...
;         for (int g = 0; g < 8; ++g) { float f[8]; unpack8(raw[g], f); float s = 0.f;
; #pragma unroll
;             for (int e = 0; e < 8; ++e) s += f[e] * f[e];
;             s = wave_sum(s); const float rs = rsqrtf(s * (1.f / 512.f) + EPS);
	v_lshlrev_b32_e32 v4, 16, v184
	v_and_b32_e32 v5, 0xffff0000, v184
	v_mul_f32_e32 v8, v4, v4
	v_fmac_f32_e32 v8, v5, v5
	v_lshlrev_b32_e32 v4, 16, v185
	v_and_b32_e32 v5, 0xffff0000, v185
	v_fmac_f32_e32 v8, v4, v4
	v_fmac_f32_e32 v8, v5, v5
	v_lshlrev_b32_e32 v4, 16, v186
	v_and_b32_e32 v5, 0xffff0000, v186
	v_fmac_f32_e32 v8, v4, v4
	v_fmac_f32_e32 v8, v5, v5
	v_lshlrev_b32_e32 v4, 16, v187
	v_and_b32_e32 v5, 0xffff0000, v187
	v_fmac_f32_e32 v8, v4, v4
	v_fmac_f32_e32 v8, v5, v5
	v_lshlrev_b32_e32 v4, 16, v188
	v_and_b32_e32 v5, 0xffff0000, v188
	v_mul_f32_e32 v9, v4, v4
	v_fmac_f32_e32 v9, v5, v5
	v_lshlrev_b32_e32 v4, 16, v189
	v_and_b32_e32 v5, 0xffff0000, v189
	v_fmac_f32_e32 v9, v4, v4
	v_fmac_f32_e32 v9, v5, v5
	v_lshlrev_b32_e32 v4, 16, v190
	v_and_b32_e32 v5, 0xffff0000, v190
	v_fmac_f32_e32 v9, v4, v4
	v_fmac_f32_e32 v9, v5, v5
	v_lshlrev_b32_e32 v4, 16, v191
	v_and_b32_e32 v5, 0xffff0000, v191
	v_fmac_f32_e32 v9, v4, v4
	v_fmac_f32_e32 v9, v5, v5
	v_lshlrev_b32_e32 v4, 16, v192
	v_and_b32_e32 v5, 0xffff0000, v192
	v_mul_f32_e32 v10, v4, v4
	v_fmac_f32_e32 v10, v5, v5
	v_lshlrev_b32_e32 v4, 16, v193
	v_and_b32_e32 v5, 0xffff0000, v193
	v_fmac_f32_e32 v10, v4, v4
	v_fmac_f32_e32 v10, v5, v5
	v_lshlrev_b32_e32 v4, 16, v194
	v_and_b32_e32 v5, 0xffff0000, v194
	v_fmac_f32_e32 v10, v4, v4
	v_fmac_f32_e32 v10, v5, v5
	v_lshlrev_b32_e32 v4, 16, v195
	v_and_b32_e32 v5, 0xffff0000, v195
	v_fmac_f32_e32 v10, v4, v4
	v_fmac_f32_e32 v10, v5, v5
	v_lshlrev_b32_e32 v4, 16, v196
	v_and_b32_e32 v5, 0xffff0000, v196
	v_mul_f32_e32 v11, v4, v4
	v_fmac_f32_e32 v11, v5, v5
	v_lshlrev_b32_e32 v4, 16, v197
	v_and_b32_e32 v5, 0xffff0000, v197
	v_fmac_f32_e32 v11, v4, v4
	v_fmac_f32_e32 v11, v5, v5
	v_lshlrev_b32_e32 v4, 16, v198
	v_and_b32_e32 v5, 0xffff0000, v198
	v_fmac_f32_e32 v11, v4, v4
	v_fmac_f32_e32 v11, v5, v5
	v_lshlrev_b32_e32 v4, 16, v199
	v_and_b32_e32 v5, 0xffff0000, v199
	v_fmac_f32_e32 v11, v4, v4
	v_fmac_f32_e32 v11, v5, v5
	v_lshlrev_b32_e32 v4, 16, v200
	v_and_b32_e32 v5, 0xffff0000, v200
	v_mul_f32_e32 v12, v4, v4
	v_fmac_f32_e32 v12, v5, v5
	v_lshlrev_b32_e32 v4, 16, v201
	v_and_b32_e32 v5, 0xffff0000, v201
	v_fmac_f32_e32 v12, v4, v4
	v_fmac_f32_e32 v12, v5, v5
	v_lshlrev_b32_e32 v4, 16, v202
	v_and_b32_e32 v5, 0xffff0000, v202
	v_fmac_f32_e32 v12, v4, v4
	v_fmac_f32_e32 v12, v5, v5
	v_lshlrev_b32_e32 v4, 16, v203
	v_and_b32_e32 v5, 0xffff0000, v203
	v_fmac_f32_e32 v12, v4, v4
	v_fmac_f32_e32 v12, v5, v5
	v_lshlrev_b32_e32 v4, 16, v204
	v_and_b32_e32 v5, 0xffff0000, v204
	v_mul_f32_e32 v13, v4, v4
	v_fmac_f32_e32 v13, v5, v5
	v_lshlrev_b32_e32 v4, 16, v205
	v_and_b32_e32 v5, 0xffff0000, v205
	v_fmac_f32_e32 v13, v4, v4
	v_fmac_f32_e32 v13, v5, v5
	v_lshlrev_b32_e32 v4, 16, v206
	v_and_b32_e32 v5, 0xffff0000, v206
	v_fmac_f32_e32 v13, v4, v4
	v_fmac_f32_e32 v13, v5, v5
	v_lshlrev_b32_e32 v4, 16, v207
	v_and_b32_e32 v5, 0xffff0000, v207
	v_fmac_f32_e32 v13, v4, v4
	v_fmac_f32_e32 v13, v5, v5
	v_lshlrev_b32_e32 v4, 16, v208
	v_and_b32_e32 v5, 0xffff0000, v208
	v_mul_f32_e32 v14, v4, v4
	v_fmac_f32_e32 v14, v5, v5
	v_lshlrev_b32_e32 v4, 16, v209
	v_and_b32_e32 v5, 0xffff0000, v209
	v_fmac_f32_e32 v14, v4, v4
	v_fmac_f32_e32 v14, v5, v5
	v_lshlrev_b32_e32 v4, 16, v210
	v_and_b32_e32 v5, 0xffff0000, v210
	v_fmac_f32_e32 v14, v4, v4
	v_fmac_f32_e32 v14, v5, v5
	v_lshlrev_b32_e32 v4, 16, v211
	v_and_b32_e32 v5, 0xffff0000, v211
	v_fmac_f32_e32 v14, v4, v4
	v_fmac_f32_e32 v14, v5, v5
	v_lshlrev_b32_e32 v4, 16, v212
	v_and_b32_e32 v5, 0xffff0000, v212
	v_mul_f32_e32 v15, v4, v4
	v_fmac_f32_e32 v15, v5, v5
	v_lshlrev_b32_e32 v4, 16, v213
	v_and_b32_e32 v5, 0xffff0000, v213
	v_fmac_f32_e32 v15, v4, v4
	v_fmac_f32_e32 v15, v5, v5
	v_lshlrev_b32_e32 v4, 16, v214
	v_and_b32_e32 v5, 0xffff0000, v214
	v_fmac_f32_e32 v15, v4, v4
	v_fmac_f32_e32 v15, v5, v5
	v_lshlrev_b32_e32 v4, 16, v215
	v_and_b32_e32 v5, 0xffff0000, v215
	v_fmac_f32_e32 v15, v4, v4
	v_fmac_f32_e32 v15, v5, v5
	v_add_f32_dpp v8, v8, v8 quad_perm:[1,0,3,2] row_mask:0xf bank_mask:0xf
	v_add_f32_dpp v9, v9, v9 quad_perm:[1,0,3,2] row_mask:0xf bank_mask:0xf
	v_add_f32_dpp v10, v10, v10 quad_perm:[1,0,3,2] row_mask:0xf bank_mask:0xf
	v_add_f32_dpp v11, v11, v11 quad_perm:[1,0,3,2] row_mask:0xf bank_mask:0xf
	v_add_f32_dpp v12, v12, v12 quad_perm:[1,0,3,2] row_mask:0xf bank_mask:0xf
	v_add_f32_dpp v13, v13, v13 quad_perm:[1,0,3,2] row_mask:0xf bank_mask:0xf
	v_add_f32_dpp v14, v14, v14 quad_perm:[1,0,3,2] row_mask:0xf bank_mask:0xf
	v_add_f32_dpp v15, v15, v15 quad_perm:[1,0,3,2] row_mask:0xf bank_mask:0xf
	v_add_f32_dpp v8, v8, v8 quad_perm:[2,3,0,1] row_mask:0xf bank_mask:0xf
	v_add_f32_dpp v9, v9, v9 quad_perm:[2,3,0,1] row_mask:0xf bank_mask:0xf
	v_add_f32_dpp v10, v10, v10 quad_perm:[2,3,0,1] row_mask:0xf bank_mask:0xf
	v_add_f32_dpp v11, v11, v11 quad_perm:[2,3,0,1] row_mask:0xf bank_mask:0xf
	v_add_f32_dpp v12, v12, v12 quad_perm:[2,3,0,1] row_mask:0xf bank_mask:0xf
	v_add_f32_dpp v13, v13, v13 quad_perm:[2,3,0,1] row_mask:0xf bank_mask:0xf
	v_add_f32_dpp v14, v14, v14 quad_perm:[2,3,0,1] row_mask:0xf bank_mask:0xf
	v_add_f32_dpp v15, v15, v15 quad_perm:[2,3,0,1] row_mask:0xf bank_mask:0xf
	v_add_f32_dpp v8, v8, v8 row_half_mirror row_mask:0xf bank_mask:0xf
	v_add_f32_dpp v9, v9, v9 row_half_mirror row_mask:0xf bank_mask:0xf
	v_add_f32_dpp v10, v10, v10 row_half_mirror row_mask:0xf bank_mask:0xf
	v_add_f32_dpp v11, v11, v11 row_half_mirror row_mask:0xf bank_mask:0xf
	v_add_f32_dpp v12, v12, v12 row_half_mirror row_mask:0xf bank_mask:0xf
	v_add_f32_dpp v13, v13, v13 row_half_mirror row_mask:0xf bank_mask:0xf
	v_add_f32_dpp v14, v14, v14 row_half_mirror row_mask:0xf bank_mask:0xf
; #define GAS __attribute__((address_space(1)))
; __device__ __forceinline__ v4u pack8(const float (&f)[8]) { v4u o; o.x = cvt_pk_bf16(f[0], f[1]); o.y = cvt_pk_bf16(f[2], f[3]); o.z = cvt_pk_bf16(f[4], f[5]); o.w = cvt_pk_bf16(f[6], f[7]); return o; }
; __device__ __forceinline__ void phase_gnorm(const Params& P, int seg) {
;     ...
;             s = wave_sum(s); const float rs = rsqrtf(s * (1.f / 512.f) + EPS);
; #pragma unroll
;             for (int e = 0; e < 8; ++e) f[e] *= rs;
;             *(GAS v4u*)(p + g * 512) = pack8(f); } }
	v_add_f32_dpp v15, v15, v15 row_half_mirror row_mask:0xf bank_mask:0xf
	v_add_f32_dpp v8, v8, v8 row_mirror row_mask:0xf bank_mask:0xf
	v_add_f32_dpp v9, v9, v9 row_mirror row_mask:0xf bank_mask:0xf
	v_add_f32_dpp v10, v10, v10 row_mirror row_mask:0xf bank_mask:0xf
	v_add_f32_dpp v11, v11, v11 row_mirror row_mask:0xf bank_mask:0xf
	v_add_f32_dpp v12, v12, v12 row_mirror row_mask:0xf bank_mask:0xf
	v_add_f32_dpp v13, v13, v13 row_mirror row_mask:0xf bank_mask:0xf
	v_add_f32_dpp v14, v14, v14 row_mirror row_mask:0xf bank_mask:0xf
	v_add_f32_dpp v15, v15, v15 row_mirror row_mask:0xf bank_mask:0xf
	v_add_f32_dpp v8, v8, v8 row_bcast:15 row_mask:0xa bank_mask:0xf
	v_add_f32_dpp v9, v9, v9 row_bcast:15 row_mask:0xa bank_mask:0xf
	v_add_f32_dpp v10, v10, v10 row_bcast:15 row_mask:0xa bank_mask:0xf
	v_add_f32_dpp v11, v11, v11 row_bcast:15 row_mask:0xa bank_mask:0xf
	v_add_f32_dpp v12, v12, v12 row_bcast:15 row_mask:0xa bank_mask:0xf
	v_add_f32_dpp v13, v13, v13 row_bcast:15 row_mask:0xa bank_mask:0xf
	v_add_f32_dpp v14, v14, v14 row_bcast:15 row_mask:0xa bank_mask:0xf
	v_add_f32_dpp v15, v15, v15 row_bcast:15 row_mask:0xa bank_mask:0xf
	v_add_f32_dpp v8, v8, v8 row_bcast:31 row_mask:0xc bank_mask:0xf
	v_add_f32_dpp v9, v9, v9 row_bcast:31 row_mask:0xc bank_mask:0xf
	v_add_f32_dpp v10, v10, v10 row_bcast:31 row_mask:0xc bank_mask:0xf
	v_add_f32_dpp v11, v11, v11 row_bcast:31 row_mask:0xc bank_mask:0xf
	v_add_f32_dpp v12, v12, v12 row_bcast:31 row_mask:0xc bank_mask:0xf
	v_add_f32_dpp v13, v13, v13 row_bcast:31 row_mask:0xc bank_mask:0xf
	v_add_f32_dpp v14, v14, v14 row_bcast:31 row_mask:0xc bank_mask:0xf
	v_add_f32_dpp v15, v15, v15 row_bcast:31 row_mask:0xc bank_mask:0xf
	s_nop 1
	v_readlane_b32 s68, v8, 63
	v_readlane_b32 s69, v9, 63
	v_readlane_b32 s70, v10, 63
	v_readlane_b32 s71, v11, 63
	v_readlane_b32 s72, v12, 63
	v_readlane_b32 s73, v13, 63
	v_readlane_b32 s74, v14, 63
	v_readlane_b32 s75, v15, 63
	s_nop 1
	v_mov_b32_e32 v16, s68
	v_mov_b32_e32 v17, s69
	v_mov_b32_e32 v18, s70
	v_mov_b32_e32 v19, s71
	v_mov_b32_e32 v20, s72
	v_mov_b32_e32 v21, s73
	v_mov_b32_e32 v22, s74
	v_mov_b32_e32 v23, s75
	v_fmamk_f32 v16, v16, 0x3b000000, v176
	v_fmamk_f32 v17, v17, 0x3b000000, v176
	v_fmamk_f32 v18, v18, 0x3b000000, v176
	v_fmamk_f32 v19, v19, 0x3b000000, v176
	v_fmamk_f32 v20, v20, 0x3b000000, v176
	v_fmamk_f32 v21, v21, 0x3b000000, v176
	v_fmamk_f32 v22, v22, 0x3b000000, v176
	v_fmamk_f32 v23, v23, 0x3b000000, v176
	v_rsq_f32_e32 v16, v16
	v_rsq_f32_e32 v17, v17
	v_rsq_f32_e32 v18, v18
	v_rsq_f32_e32 v19, v19
	v_rsq_f32_e32 v20, v20
	v_rsq_f32_e32 v21, v21
	v_rsq_f32_e32 v22, v22
	v_rsq_f32_e32 v23, v23
	v_lshlrev_b32_e32 v4, 16, v184
	v_and_b32_e32 v5, 0xffff0000, v184
	v_mul_f32_e32 v4, v16, v4
	v_mul_f32_e32 v5, v16, v5
	v_cvt_pk_bf16_f32 v184, v4, v5
	v_lshlrev_b32_e32 v4, 16, v185
	v_and_b32_e32 v5, 0xffff0000, v185
	v_mul_f32_e32 v4, v16, v4
	v_mul_f32_e32 v5, v16, v5
	v_cvt_pk_bf16_f32 v185, v4, v5
	v_lshlrev_b32_e32 v4, 16, v186
	v_and_b32_e32 v5, 0xffff0000, v186
	v_mul_f32_e32 v4, v16, v4
	v_mul_f32_e32 v5, v16, v5
	v_cvt_pk_bf16_f32 v186, v4, v5
	v_lshlrev_b32_e32 v4, 16, v187
	v_and_b32_e32 v5, 0xffff0000, v187
	v_mul_f32_e32 v4, v16, v4
	v_mul_f32_e32 v5, v16, v5
	v_cvt_pk_bf16_f32 v187, v4, v5
	global_store_dwordx4 v24, v[184:187], s[66:67]
	v_lshlrev_b32_e32 v4, 16, v188
	v_and_b32_e32 v5, 0xffff0000, v188
	v_mul_f32_e32 v4, v17, v4
	v_mul_f32_e32 v5, v17, v5
	v_cvt_pk_bf16_f32 v188, v4, v5
	v_lshlrev_b32_e32 v4, 16, v189
	v_and_b32_e32 v5, 0xffff0000, v189
	v_mul_f32_e32 v4, v17, v4
	v_mul_f32_e32 v5, v17, v5
	v_cvt_pk_bf16_f32 v189, v4, v5
	v_lshlrev_b32_e32 v4, 16, v190
	v_and_b32_e32 v5, 0xffff0000, v190
	v_mul_f32_e32 v4, v17, v4
	v_mul_f32_e32 v5, v17, v5
	v_cvt_pk_bf16_f32 v190, v4, v5
	v_lshlrev_b32_e32 v4, 16, v191
	v_and_b32_e32 v5, 0xffff0000, v191
	v_mul_f32_e32 v4, v17, v4
	v_mul_f32_e32 v5, v17, v5
	v_cvt_pk_bf16_f32 v191, v4, v5
	global_store_dwordx4 v24, v[188:191], s[66:67] offset:1024
	v_lshlrev_b32_e32 v4, 16, v192
	v_and_b32_e32 v5, 0xffff0000, v192
	v_mul_f32_e32 v4, v18, v4
	v_mul_f32_e32 v5, v18, v5
	v_cvt_pk_bf16_f32 v192, v4, v5
	v_lshlrev_b32_e32 v4, 16, v193
	v_and_b32_e32 v5, 0xffff0000, v193
	v_mul_f32_e32 v4, v18, v4
	v_mul_f32_e32 v5, v18, v5
	v_cvt_pk_bf16_f32 v193, v4, v5
	v_lshlrev_b32_e32 v4, 16, v194
	v_and_b32_e32 v5, 0xffff0000, v194
	v_mul_f32_e32 v4, v18, v4
	v_mul_f32_e32 v5, v18, v5
	v_cvt_pk_bf16_f32 v194, v4, v5
	v_lshlrev_b32_e32 v4, 16, v195
	v_and_b32_e32 v5, 0xffff0000, v195
	v_mul_f32_e32 v4, v18, v4
	v_mul_f32_e32 v5, v18, v5
	v_cvt_pk_bf16_f32 v195, v4, v5
	global_store_dwordx4 v24, v[192:195], s[66:67] offset:2048
	v_lshlrev_b32_e32 v4, 16, v196
	v_and_b32_e32 v5, 0xffff0000, v196
	v_mul_f32_e32 v4, v19, v4
	v_mul_f32_e32 v5, v19, v5
	v_cvt_pk_bf16_f32 v196, v4, v5
	v_lshlrev_b32_e32 v4, 16, v197
	v_and_b32_e32 v5, 0xffff0000, v197
	v_mul_f32_e32 v4, v19, v4
	v_mul_f32_e32 v5, v19, v5
	v_cvt_pk_bf16_f32 v197, v4, v5
	v_lshlrev_b32_e32 v4, 16, v198
	v_and_b32_e32 v5, 0xffff0000, v198
	v_mul_f32_e32 v4, v19, v4
	v_mul_f32_e32 v5, v19, v5
	v_cvt_pk_bf16_f32 v198, v4, v5
	v_lshlrev_b32_e32 v4, 16, v199
	v_and_b32_e32 v5, 0xffff0000, v199
	v_mul_f32_e32 v4, v19, v4
	v_mul_f32_e32 v5, v19, v5
	v_cvt_pk_bf16_f32 v199, v4, v5
	global_store_dwordx4 v24, v[196:199], s[66:67] offset:3072
	v_lshlrev_b32_e32 v4, 16, v200
	v_and_b32_e32 v5, 0xffff0000, v200
	v_mul_f32_e32 v4, v20, v4
	v_mul_f32_e32 v5, v20, v5
	v_cvt_pk_bf16_f32 v200, v4, v5
	v_lshlrev_b32_e32 v4, 16, v201
	v_and_b32_e32 v5, 0xffff0000, v201
	v_mul_f32_e32 v4, v20, v4
	v_mul_f32_e32 v5, v20, v5
	v_cvt_pk_bf16_f32 v201, v4, v5
; #define GAS __attribute__((address_space(1)))
; __device__ __forceinline__ void unpack8(const v4u v, float (&f)[8]) { f[0] = bflo(v.x); f[1] = bfhi(v.x); f[2] = bflo(v.y); f[3] = bfhi(v.y); f[4] = bflo(v.z); f[5] = bfhi(v.z); f[6] = bflo(v.w); f[7] = bfhi(v.w); }
; __device__ __forceinline__ v4u pack8(const float (&f)[8]) { v4u o; o.x = cvt_pk_bf16(f[0], f[1]); o.y = cvt_pk_bf16(f[2], f[3]); o.z = cvt_pk_bf16(f[4], f[5]); o.w = cvt_pk_bf16(f[6], f[7]); return o; }
; __device__ __forceinline__ void phase_gnorm(const Params& P, int seg) {
;     ...
;     for (int rr = gw; rr < nrows; rr += NGW) { const int row = (rr < RS) ? rr : rr + 48; GAS bf16* p = ypre + (size_t)row * DINNER + lane * 8;
;         v4u raw[8];
; #pragma unroll
;         for (int g = 0; g < 8; ++g) raw[g] = *(const GAS v4u*)(p + g * 512);
; #pragma unroll
;         for (int g = 0; g < 8; ++g) { float f[8]; unpack8(raw[g], f); float s = 0.f;
; #pragma unroll
;             for (int e = 0; e < 8; ++e) s += f[e] * f[e];
;             s = wave_sum(s); const float rs = rsqrtf(s * (1.f / 512.f) + EPS);
; #pragma unroll
;             for (int e = 0; e < 8; ++e) f[e] *= rs;
;             *(GAS v4u*)(p + g * 512) = pack8(f); } }
	v_lshlrev_b32_e32 v4, 16, v202
	v_and_b32_e32 v5, 0xffff0000, v202
	v_mul_f32_e32 v4, v20, v4
	v_mul_f32_e32 v5, v20, v5
	v_cvt_pk_bf16_f32 v202, v4, v5
	v_lshlrev_b32_e32 v4, 16, v203
	v_and_b32_e32 v5, 0xffff0000, v203
	v_mul_f32_e32 v4, v20, v4
	v_mul_f32_e32 v5, v20, v5
	v_cvt_pk_bf16_f32 v203, v4, v5
	global_store_dwordx4 v25, v[200:203], s[66:67]
	v_lshlrev_b32_e32 v4, 16, v204
	v_and_b32_e32 v5, 0xffff0000, v204
	v_mul_f32_e32 v4, v21, v4
	v_mul_f32_e32 v5, v21, v5
	v_cvt_pk_bf16_f32 v204, v4, v5
	v_lshlrev_b32_e32 v4, 16, v205
	v_and_b32_e32 v5, 0xffff0000, v205
	v_mul_f32_e32 v4, v21, v4
	v_mul_f32_e32 v5, v21, v5
	v_cvt_pk_bf16_f32 v205, v4, v5
	v_lshlrev_b32_e32 v4, 16, v206
	v_and_b32_e32 v5, 0xffff0000, v206
	v_mul_f32_e32 v4, v21, v4
	v_mul_f32_e32 v5, v21, v5
	v_cvt_pk_bf16_f32 v206, v4, v5
	v_lshlrev_b32_e32 v4, 16, v207
	v_and_b32_e32 v5, 0xffff0000, v207
	v_mul_f32_e32 v4, v21, v4
	v_mul_f32_e32 v5, v21, v5
	v_cvt_pk_bf16_f32 v207, v4, v5
	global_store_dwordx4 v25, v[204:207], s[66:67] offset:1024
	v_lshlrev_b32_e32 v4, 16, v208
	v_and_b32_e32 v5, 0xffff0000, v208
	v_mul_f32_e32 v4, v22, v4
	v_mul_f32_e32 v5, v22, v5
	v_cvt_pk_bf16_f32 v208, v4, v5
	v_lshlrev_b32_e32 v4, 16, v209
	v_and_b32_e32 v5, 0xffff0000, v209
	v_mul_f32_e32 v4, v22, v4
	v_mul_f32_e32 v5, v22, v5
	v_cvt_pk_bf16_f32 v209, v4, v5
	v_lshlrev_b32_e32 v4, 16, v210
	v_and_b32_e32 v5, 0xffff0000, v210
	v_mul_f32_e32 v4, v22, v4
	v_mul_f32_e32 v5, v22, v5
	v_cvt_pk_bf16_f32 v210, v4, v5
	v_lshlrev_b32_e32 v4, 16, v211
	v_and_b32_e32 v5, 0xffff0000, v211
	v_mul_f32_e32 v4, v22, v4
	v_mul_f32_e32 v5, v22, v5
	v_cvt_pk_bf16_f32 v211, v4, v5
	global_store_dwordx4 v25, v[208:211], s[66:67] offset:2048
	v_lshlrev_b32_e32 v4, 16, v212
	v_and_b32_e32 v5, 0xffff0000, v212
	v_mul_f32_e32 v4, v23, v4
	v_mul_f32_e32 v5, v23, v5
	v_cvt_pk_bf16_f32 v212, v4, v5
	v_lshlrev_b32_e32 v4, 16, v213
	v_and_b32_e32 v5, 0xffff0000, v213
	v_mul_f32_e32 v4, v23, v4
	v_mul_f32_e32 v5, v23, v5
	v_cvt_pk_bf16_f32 v213, v4, v5
	v_lshlrev_b32_e32 v4, 16, v214
	v_and_b32_e32 v5, 0xffff0000, v214
	v_mul_f32_e32 v4, v23, v4
	v_mul_f32_e32 v5, v23, v5
	v_cvt_pk_bf16_f32 v214, v4, v5
	v_lshlrev_b32_e32 v4, 16, v215
	v_and_b32_e32 v5, 0xffff0000, v215
	v_mul_f32_e32 v4, v23, v4
	v_mul_f32_e32 v5, v23, v5
	v_cvt_pk_bf16_f32 v215, v4, v5
	global_store_dwordx4 v25, v[212:215], s[66:67] offset:3072
	s_cmp_lg_u32 s65, 0
	s_cbranch_scc1 .Lgn_fast_done
	s_cmp_gt_u32 s63, 15
	s_cbranch_scc1 .Lgn_fast_done
	s_add_i32 s53, s63, 0x2030
	s_lshl_b32 s53, s53, 13
	s_add_u32 s54, s40, s53
	s_addc_u32 s55, s41, 0
	global_load_dwordx4 v[40:43], v24, s[54:55]
	global_load_dwordx4 v[44:47], v24, s[54:55] offset:1024
	global_load_dwordx4 v[48:51], v24, s[54:55] offset:2048
	global_load_dwordx4 v[52:55], v24, s[54:55] offset:3072
	global_load_dwordx4 v[56:59], v25, s[54:55]
	global_load_dwordx4 v[60:63], v25, s[54:55] offset:1024
	global_load_dwordx4 v[64:67], v25, s[54:55] offset:2048
	global_load_dwordx4 v[68:71], v25, s[54:55] offset:3072
	s_waitcnt vmcnt(0)
	v_lshlrev_b32_e32 v4, 16, v40
	v_and_b32_e32 v5, 0xffff0000, v40
	v_mul_f32_e32 v8, v4, v4
	v_fmac_f32_e32 v8, v5, v5
	v_lshlrev_b32_e32 v4, 16, v41
	v_and_b32_e32 v5, 0xffff0000, v41
	v_fmac_f32_e32 v8, v4, v4
	v_fmac_f32_e32 v8, v5, v5
	v_lshlrev_b32_e32 v4, 16, v42
	v_and_b32_e32 v5, 0xffff0000, v42
	v_fmac_f32_e32 v8, v4, v4
	v_fmac_f32_e32 v8, v5, v5
	v_lshlrev_b32_e32 v4, 16, v43
	v_and_b32_e32 v5, 0xffff0000, v43
	v_fmac_f32_e32 v8, v4, v4
	v_fmac_f32_e32 v8, v5, v5
	v_lshlrev_b32_e32 v4, 16, v44
	v_and_b32_e32 v5, 0xffff0000, v44
	v_mul_f32_e32 v9, v4, v4
	v_fmac_f32_e32 v9, v5, v5
	v_lshlrev_b32_e32 v4, 16, v45
	v_and_b32_e32 v5, 0xffff0000, v45
	v_fmac_f32_e32 v9, v4, v4
	v_fmac_f32_e32 v9, v5, v5
	v_lshlrev_b32_e32 v4, 16, v46
	v_and_b32_e32 v5, 0xffff0000, v46
	v_fmac_f32_e32 v9, v4, v4
	v_fmac_f32_e32 v9, v5, v5
	v_lshlrev_b32_e32 v4, 16, v47
	v_and_b32_e32 v5, 0xffff0000, v47
	v_fmac_f32_e32 v9, v4, v4
	v_fmac_f32_e32 v9, v5, v5
	v_lshlrev_b32_e32 v4, 16, v48
	v_and_b32_e32 v5, 0xffff0000, v48
	v_mul_f32_e32 v10, v4, v4
	v_fmac_f32_e32 v10, v5, v5
	v_lshlrev_b32_e32 v4, 16, v49
	v_and_b32_e32 v5, 0xffff0000, v49
	v_fmac_f32_e32 v10, v4, v4
	v_fmac_f32_e32 v10, v5, v5
	v_lshlrev_b32_e32 v4, 16, v50
	v_and_b32_e32 v5, 0xffff0000, v50
	v_fmac_f32_e32 v10, v4, v4
	v_fmac_f32_e32 v10, v5, v5
	v_lshlrev_b32_e32 v4, 16, v51
	v_and_b32_e32 v5, 0xffff0000, v51
	v_fmac_f32_e32 v10, v4, v4
	v_fmac_f32_e32 v10, v5, v5
	v_lshlrev_b32_e32 v4, 16, v52
	v_and_b32_e32 v5, 0xffff0000, v52
	v_mul_f32_e32 v11, v4, v4
	v_fmac_f32_e32 v11, v5, v5
	v_lshlrev_b32_e32 v4, 16, v53
	v_and_b32_e32 v5, 0xffff0000, v53
	v_fmac_f32_e32 v11, v4, v4
	v_fmac_f32_e32 v11, v5, v5
	v_lshlrev_b32_e32 v4, 16, v54
	v_and_b32_e32 v5, 0xffff0000, v54
	v_fmac_f32_e32 v11, v4, v4
	v_fmac_f32_e32 v11, v5, v5
	v_lshlrev_b32_e32 v4, 16, v55
	v_and_b32_e32 v5, 0xffff0000, v55
	v_fmac_f32_e32 v11, v4, v4
	v_fmac_f32_e32 v11, v5, v5
	v_lshlrev_b32_e32 v4, 16, v56
	v_and_b32_e32 v5, 0xffff0000, v56
	v_mul_f32_e32 v12, v4, v4
	v_fmac_f32_e32 v12, v5, v5
	v_lshlrev_b32_e32 v4, 16, v57
	v_and_b32_e32 v5, 0xffff0000, v57
	v_fmac_f32_e32 v12, v4, v4
	v_fmac_f32_e32 v12, v5, v5
	v_lshlrev_b32_e32 v4, 16, v58
	v_and_b32_e32 v5, 0xffff0000, v58
	v_fmac_f32_e32 v12, v4, v4
	v_fmac_f32_e32 v12, v5, v5
	v_lshlrev_b32_e32 v4, 16, v59
	v_and_b32_e32 v5, 0xffff0000, v59
	v_fmac_f32_e32 v12, v4, v4
	v_fmac_f32_e32 v12, v5, v5
	v_lshlrev_b32_e32 v4, 16, v60
	v_and_b32_e32 v5, 0xffff0000, v60
	v_mul_f32_e32 v13, v4, v4
	v_fmac_f32_e32 v13, v5, v5
	v_lshlrev_b32_e32 v4, 16, v61
	v_and_b32_e32 v5, 0xffff0000, v61
; #define GAS __attribute__((address_space(1)))
; __device__ __forceinline__ void unpack8(const v4u v, float (&f)[8]) { f[0] = bflo(v.x); f[1] = bfhi(v.x); f[2] = bflo(v.y); f[3] = bfhi(v.y); f[4] = bflo(v.z); f[5] = bfhi(v.z); f[6] = bflo(v.w); f[7] = bfhi(v.w); }
; __device__ __forceinline__ v4u pack8(const float (&f)[8]) { v4u o; o.x = cvt_pk_bf16(f[0], f[1]); o.y = cvt_pk_bf16(f[2], f[3]); o.z = cvt_pk_bf16(f[4], f[5]); o.w = cvt_pk_bf16(f[6], f[7]); return o; }
; __device__ __forceinline__ float wave_sum(float v) {
; #pragma unroll
;     for (int o = 1; o < 64; o <<= 1) v += __shfl_xor(v, o);
;     return v;
; __device__ __forceinline__ void phase_gnorm(const Params& P, int seg) {
;     ...
;         for (int g = 0; g < 8; ++g) { float f[8]; unpack8(raw[g], f); float s = 0.f;
; #pragma unroll
;             for (int e = 0; e < 8; ++e) s += f[e] * f[e];
;             s = wave_sum(s); const float rs = rsqrtf(s * (1.f / 512.f) + EPS);
; #pragma unroll
;             for (int e = 0; e < 8; ++e) f[e] *= rs;
;             *(GAS v4u*)(p + g * 512) = pack8(f); } }
	v_fmac_f32_e32 v13, v4, v4
	v_fmac_f32_e32 v13, v5, v5
	v_lshlrev_b32_e32 v4, 16, v62
	v_and_b32_e32 v5, 0xffff0000, v62
	v_fmac_f32_e32 v13, v4, v4
	v_fmac_f32_e32 v13, v5, v5
	v_lshlrev_b32_e32 v4, 16, v63
	v_and_b32_e32 v5, 0xffff0000, v63
	v_fmac_f32_e32 v13, v4, v4
	v_fmac_f32_e32 v13, v5, v5
	v_lshlrev_b32_e32 v4, 16, v64
	v_and_b32_e32 v5, 0xffff0000, v64
	v_mul_f32_e32 v14, v4, v4
	v_fmac_f32_e32 v14, v5, v5
	v_lshlrev_b32_e32 v4, 16, v65
	v_and_b32_e32 v5, 0xffff0000, v65
	v_fmac_f32_e32 v14, v4, v4
	v_fmac_f32_e32 v14, v5, v5
	v_lshlrev_b32_e32 v4, 16, v66
	v_and_b32_e32 v5, 0xffff0000, v66
	v_fmac_f32_e32 v14, v4, v4
	v_fmac_f32_e32 v14, v5, v5
	v_lshlrev_b32_e32 v4, 16, v67
	v_and_b32_e32 v5, 0xffff0000, v67
	v_fmac_f32_e32 v14, v4, v4
	v_fmac_f32_e32 v14, v5, v5
	v_lshlrev_b32_e32 v4, 16, v68
	v_and_b32_e32 v5, 0xffff0000, v68
	v_mul_f32_e32 v15, v4, v4
	v_fmac_f32_e32 v15, v5, v5
	v_lshlrev_b32_e32 v4, 16, v69
	v_and_b32_e32 v5, 0xffff0000, v69
	v_fmac_f32_e32 v15, v4, v4
	v_fmac_f32_e32 v15, v5, v5
	v_lshlrev_b32_e32 v4, 16, v70
	v_and_b32_e32 v5, 0xffff0000, v70
	v_fmac_f32_e32 v15, v4, v4
	v_fmac_f32_e32 v15, v5, v5
	v_lshlrev_b32_e32 v4, 16, v71
	v_and_b32_e32 v5, 0xffff0000, v71
	v_fmac_f32_e32 v15, v4, v4
	v_fmac_f32_e32 v15, v5, v5
	v_add_f32_dpp v8, v8, v8 quad_perm:[1,0,3,2] row_mask:0xf bank_mask:0xf
	v_add_f32_dpp v9, v9, v9 quad_perm:[1,0,3,2] row_mask:0xf bank_mask:0xf
	v_add_f32_dpp v10, v10, v10 quad_perm:[1,0,3,2] row_mask:0xf bank_mask:0xf
	v_add_f32_dpp v11, v11, v11 quad_perm:[1,0,3,2] row_mask:0xf bank_mask:0xf
	v_add_f32_dpp v12, v12, v12 quad_perm:[1,0,3,2] row_mask:0xf bank_mask:0xf
	v_add_f32_dpp v13, v13, v13 quad_perm:[1,0,3,2] row_mask:0xf bank_mask:0xf
	v_add_f32_dpp v14, v14, v14 quad_perm:[1,0,3,2] row_mask:0xf bank_mask:0xf
	v_add_f32_dpp v15, v15, v15 quad_perm:[1,0,3,2] row_mask:0xf bank_mask:0xf
	v_add_f32_dpp v8, v8, v8 quad_perm:[2,3,0,1] row_mask:0xf bank_mask:0xf
	v_add_f32_dpp v9, v9, v9 quad_perm:[2,3,0,1] row_mask:0xf bank_mask:0xf
	v_add_f32_dpp v10, v10, v10 quad_perm:[2,3,0,1] row_mask:0xf bank_mask:0xf
	v_add_f32_dpp v11, v11, v11 quad_perm:[2,3,0,1] row_mask:0xf bank_mask:0xf
	v_add_f32_dpp v12, v12, v12 quad_perm:[2,3,0,1] row_mask:0xf bank_mask:0xf
	v_add_f32_dpp v13, v13, v13 quad_perm:[2,3,0,1] row_mask:0xf bank_mask:0xf
	v_add_f32_dpp v14, v14, v14 quad_perm:[2,3,0,1] row_mask:0xf bank_mask:0xf
	v_add_f32_dpp v15, v15, v15 quad_perm:[2,3,0,1] row_mask:0xf bank_mask:0xf
	v_add_f32_dpp v8, v8, v8 row_half_mirror row_mask:0xf bank_mask:0xf
	v_add_f32_dpp v9, v9, v9 row_half_mirror row_mask:0xf bank_mask:0xf
	v_add_f32_dpp v10, v10, v10 row_half_mirror row_mask:0xf bank_mask:0xf
	v_add_f32_dpp v11, v11, v11 row_half_mirror row_mask:0xf bank_mask:0xf
	v_add_f32_dpp v12, v12, v12 row_half_mirror row_mask:0xf bank_mask:0xf
	v_add_f32_dpp v13, v13, v13 row_half_mirror row_mask:0xf bank_mask:0xf
	v_add_f32_dpp v14, v14, v14 row_half_mirror row_mask:0xf bank_mask:0xf
	v_add_f32_dpp v15, v15, v15 row_half_mirror row_mask:0xf bank_mask:0xf
	v_add_f32_dpp v8, v8, v8 row_mirror row_mask:0xf bank_mask:0xf
	v_add_f32_dpp v9, v9, v9 row_mirror row_mask:0xf bank_mask:0xf
	v_add_f32_dpp v10, v10, v10 row_mirror row_mask:0xf bank_mask:0xf
	v_add_f32_dpp v11, v11, v11 row_mirror row_mask:0xf bank_mask:0xf
	v_add_f32_dpp v12, v12, v12 row_mirror row_mask:0xf bank_mask:0xf
	v_add_f32_dpp v13, v13, v13 row_mirror row_mask:0xf bank_mask:0xf
	v_add_f32_dpp v14, v14, v14 row_mirror row_mask:0xf bank_mask:0xf
	v_add_f32_dpp v15, v15, v15 row_mirror row_mask:0xf bank_mask:0xf
	v_add_f32_dpp v8, v8, v8 row_bcast:15 row_mask:0xa bank_mask:0xf
	v_add_f32_dpp v9, v9, v9 row_bcast:15 row_mask:0xa bank_mask:0xf
	v_add_f32_dpp v10, v10, v10 row_bcast:15 row_mask:0xa bank_mask:0xf
	v_add_f32_dpp v11, v11, v11 row_bcast:15 row_mask:0xa bank_mask:0xf
	v_add_f32_dpp v12, v12, v12 row_bcast:15 row_mask:0xa bank_mask:0xf
	v_add_f32_dpp v13, v13, v13 row_bcast:15 row_mask:0xa bank_mask:0xf
	v_add_f32_dpp v14, v14, v14 row_bcast:15 row_mask:0xa bank_mask:0xf
	v_add_f32_dpp v15, v15, v15 row_bcast:15 row_mask:0xa bank_mask:0xf
	v_add_f32_dpp v8, v8, v8 row_bcast:31 row_mask:0xc bank_mask:0xf
	v_add_f32_dpp v9, v9, v9 row_bcast:31 row_mask:0xc bank_mask:0xf
	v_add_f32_dpp v10, v10, v10 row_bcast:31 row_mask:0xc bank_mask:0xf
	v_add_f32_dpp v11, v11, v11 row_bcast:31 row_mask:0xc bank_mask:0xf
	v_add_f32_dpp v12, v12, v12 row_bcast:31 row_mask:0xc bank_mask:0xf
	v_add_f32_dpp v13, v13, v13 row_bcast:31 row_mask:0xc bank_mask:0xf
	v_add_f32_dpp v14, v14, v14 row_bcast:31 row_mask:0xc bank_mask:0xf
	v_add_f32_dpp v15, v15, v15 row_bcast:31 row_mask:0xc bank_mask:0xf
	s_nop 1
	v_readlane_b32 s68, v8, 63
	v_readlane_b32 s69, v9, 63
	v_readlane_b32 s70, v10, 63
	v_readlane_b32 s71, v11, 63
	v_readlane_b32 s72, v12, 63
	v_readlane_b32 s73, v13, 63
	v_readlane_b32 s74, v14, 63
	v_readlane_b32 s75, v15, 63
	s_nop 1
	v_mov_b32_e32 v16, s68
	v_mov_b32_e32 v17, s69
	v_mov_b32_e32 v18, s70
	v_mov_b32_e32 v19, s71
	v_mov_b32_e32 v20, s72
	v_mov_b32_e32 v21, s73
	v_mov_b32_e32 v22, s74
	v_mov_b32_e32 v23, s75
	v_fmamk_f32 v16, v16, 0x3b000000, v176
	v_fmamk_f32 v17, v17, 0x3b000000, v176
	v_fmamk_f32 v18, v18, 0x3b000000, v176
	v_fmamk_f32 v19, v19, 0x3b000000, v176
	v_fmamk_f32 v20, v20, 0x3b000000, v176
	v_fmamk_f32 v21, v21, 0x3b000000, v176
	v_fmamk_f32 v22, v22, 0x3b000000, v176
	v_fmamk_f32 v23, v23, 0x3b000000, v176
	v_rsq_f32_e32 v16, v16
	v_rsq_f32_e32 v17, v17
; #define GAS __attribute__((address_space(1)))
; __device__ __forceinline__ v4u pack8(const float (&f)[8]) { v4u o; o.x = cvt_pk_bf16(f[0], f[1]); o.y = cvt_pk_bf16(f[2], f[3]); o.z = cvt_pk_bf16(f[4], f[5]); o.w = cvt_pk_bf16(f[6], f[7]); return o; }
; __device__ __forceinline__ void phase_gnorm(const Params& P, int seg) {
;     ...
;             s = wave_sum(s); const float rs = rsqrtf(s * (1.f / 512.f) + EPS);
; #pragma unroll
;             for (int e = 0; e < 8; ++e) f[e] *= rs;
;             *(GAS v4u*)(p + g * 512) = pack8(f); } }
	v_rsq_f32_e32 v18, v18
	v_rsq_f32_e32 v19, v19
	v_rsq_f32_e32 v20, v20
	v_rsq_f32_e32 v21, v21
	v_rsq_f32_e32 v22, v22
	v_rsq_f32_e32 v23, v23
	v_lshlrev_b32_e32 v4, 16, v40
	v_and_b32_e32 v5, 0xffff0000, v40
	v_mul_f32_e32 v4, v16, v4
	v_mul_f32_e32 v5, v16, v5
	v_cvt_pk_bf16_f32 v40, v4, v5
	v_lshlrev_b32_e32 v4, 16, v41
	v_and_b32_e32 v5, 0xffff0000, v41
	v_mul_f32_e32 v4, v16, v4
	v_mul_f32_e32 v5, v16, v5
	v_cvt_pk_bf16_f32 v41, v4, v5
	v_lshlrev_b32_e32 v4, 16, v42
	v_and_b32_e32 v5, 0xffff0000, v42
	v_mul_f32_e32 v4, v16, v4
	v_mul_f32_e32 v5, v16, v5
	v_cvt_pk_bf16_f32 v42, v4, v5
	v_lshlrev_b32_e32 v4, 16, v43
	v_and_b32_e32 v5, 0xffff0000, v43
	v_mul_f32_e32 v4, v16, v4
	v_mul_f32_e32 v5, v16, v5
	v_cvt_pk_bf16_f32 v43, v4, v5
	global_store_dwordx4 v24, v[40:43], s[54:55]
	v_lshlrev_b32_e32 v4, 16, v44
	v_and_b32_e32 v5, 0xffff0000, v44
	v_mul_f32_e32 v4, v17, v4
	v_mul_f32_e32 v5, v17, v5
	v_cvt_pk_bf16_f32 v44, v4, v5
	v_lshlrev_b32_e32 v4, 16, v45
	v_and_b32_e32 v5, 0xffff0000, v45
	v_mul_f32_e32 v4, v17, v4
	v_mul_f32_e32 v5, v17, v5
	v_cvt_pk_bf16_f32 v45, v4, v5
	v_lshlrev_b32_e32 v4, 16, v46
	v_and_b32_e32 v5, 0xffff0000, v46
	v_mul_f32_e32 v4, v17, v4
	v_mul_f32_e32 v5, v17, v5
	v_cvt_pk_bf16_f32 v46, v4, v5
	v_lshlrev_b32_e32 v4, 16, v47
	v_and_b32_e32 v5, 0xffff0000, v47
	v_mul_f32_e32 v4, v17, v4
	v_mul_f32_e32 v5, v17, v5
	v_cvt_pk_bf16_f32 v47, v4, v5
	global_store_dwordx4 v24, v[44:47], s[54:55] offset:1024
	v_lshlrev_b32_e32 v4, 16, v48
	v_and_b32_e32 v5, 0xffff0000, v48
	v_mul_f32_e32 v4, v18, v4
	v_mul_f32_e32 v5, v18, v5
	v_cvt_pk_bf16_f32 v48, v4, v5
	v_lshlrev_b32_e32 v4, 16, v49
	v_and_b32_e32 v5, 0xffff0000, v49
	v_mul_f32_e32 v4, v18, v4
	v_mul_f32_e32 v5, v18, v5
	v_cvt_pk_bf16_f32 v49, v4, v5
	v_lshlrev_b32_e32 v4, 16, v50
	v_and_b32_e32 v5, 0xffff0000, v50
	v_mul_f32_e32 v4, v18, v4
	v_mul_f32_e32 v5, v18, v5
	v_cvt_pk_bf16_f32 v50, v4, v5
	v_lshlrev_b32_e32 v4, 16, v51
	v_and_b32_e32 v5, 0xffff0000, v51
	v_mul_f32_e32 v4, v18, v4
	v_mul_f32_e32 v5, v18, v5
	v_cvt_pk_bf16_f32 v51, v4, v5
	global_store_dwordx4 v24, v[48:51], s[54:55] offset:2048
	v_lshlrev_b32_e32 v4, 16, v52
	v_and_b32_e32 v5, 0xffff0000, v52
	v_mul_f32_e32 v4, v19, v4
	v_mul_f32_e32 v5, v19, v5
	v_cvt_pk_bf16_f32 v52, v4, v5
	v_lshlrev_b32_e32 v4, 16, v53
	v_and_b32_e32 v5, 0xffff0000, v53
	v_mul_f32_e32 v4, v19, v4
	v_mul_f32_e32 v5, v19, v5
	v_cvt_pk_bf16_f32 v53, v4, v5
	v_lshlrev_b32_e32 v4, 16, v54
	v_and_b32_e32 v5, 0xffff0000, v54
	v_mul_f32_e32 v4, v19, v4
	v_mul_f32_e32 v5, v19, v5
	v_cvt_pk_bf16_f32 v54, v4, v5
	v_lshlrev_b32_e32 v4, 16, v55
	v_and_b32_e32 v5, 0xffff0000, v55
	v_mul_f32_e32 v4, v19, v4
	v_mul_f32_e32 v5, v19, v5
	v_cvt_pk_bf16_f32 v55, v4, v5
	global_store_dwordx4 v24, v[52:55], s[54:55] offset:3072
	v_lshlrev_b32_e32 v4, 16, v56
	v_and_b32_e32 v5, 0xffff0000, v56
	v_mul_f32_e32 v4, v20, v4
	v_mul_f32_e32 v5, v20, v5
	v_cvt_pk_bf16_f32 v56, v4, v5
	v_lshlrev_b32_e32 v4, 16, v57
	v_and_b32_e32 v5, 0xffff0000, v57
	v_mul_f32_e32 v4, v20, v4
	v_mul_f32_e32 v5, v20, v5
	v_cvt_pk_bf16_f32 v57, v4, v5
	v_lshlrev_b32_e32 v4, 16, v58
	v_and_b32_e32 v5, 0xffff0000, v58
	v_mul_f32_e32 v4, v20, v4
	v_mul_f32_e32 v5, v20, v5
	v_cvt_pk_bf16_f32 v58, v4, v5
	v_lshlrev_b32_e32 v4, 16, v59
	v_and_b32_e32 v5, 0xffff0000, v59
	v_mul_f32_e32 v4, v20, v4
	v_mul_f32_e32 v5, v20, v5
	v_cvt_pk_bf16_f32 v59, v4, v5
	global_store_dwordx4 v25, v[56:59], s[54:55]
	v_lshlrev_b32_e32 v4, 16, v60
	v_and_b32_e32 v5, 0xffff0000, v60
	v_mul_f32_e32 v4, v21, v4
	v_mul_f32_e32 v5, v21, v5
	v_cvt_pk_bf16_f32 v60, v4, v5
	v_lshlrev_b32_e32 v4, 16, v61
	v_and_b32_e32 v5, 0xffff0000, v61
	v_mul_f32_e32 v4, v21, v4
	v_mul_f32_e32 v5, v21, v5
	v_cvt_pk_bf16_f32 v61, v4, v5
	v_lshlrev_b32_e32 v4, 16, v62
	v_and_b32_e32 v5, 0xffff0000, v62
	v_mul_f32_e32 v4, v21, v4
	v_mul_f32_e32 v5, v21, v5
	v_cvt_pk_bf16_f32 v62, v4, v5
	v_lshlrev_b32_e32 v4, 16, v63
	v_and_b32_e32 v5, 0xffff0000, v63
	v_mul_f32_e32 v4, v21, v4
	v_mul_f32_e32 v5, v21, v5
	v_cvt_pk_bf16_f32 v63, v4, v5
	global_store_dwordx4 v25, v[60:63], s[54:55] offset:1024
	v_lshlrev_b32_e32 v4, 16, v64
	v_and_b32_e32 v5, 0xffff0000, v64
	v_mul_f32_e32 v4, v22, v4
	v_mul_f32_e32 v5, v22, v5
	v_cvt_pk_bf16_f32 v64, v4, v5
	v_lshlrev_b32_e32 v4, 16, v65
	v_and_b32_e32 v5, 0xffff0000, v65
	v_mul_f32_e32 v4, v22, v4
	v_mul_f32_e32 v5, v22, v5
	v_cvt_pk_bf16_f32 v65, v4, v5
	v_lshlrev_b32_e32 v4, 16, v66
	v_and_b32_e32 v5, 0xffff0000, v66
	v_mul_f32_e32 v4, v22, v4
	v_mul_f32_e32 v5, v22, v5
	v_cvt_pk_bf16_f32 v66, v4, v5
	v_lshlrev_b32_e32 v4, 16, v67
	v_and_b32_e32 v5, 0xffff0000, v67
	v_mul_f32_e32 v4, v22, v4
	v_mul_f32_e32 v5, v22, v5
	v_cvt_pk_bf16_f32 v67, v4, v5
	global_store_dwordx4 v25, v[64:67], s[54:55] offset:2048
	v_lshlrev_b32_e32 v4, 16, v68
	v_and_b32_e32 v5, 0xffff0000, v68
	v_mul_f32_e32 v4, v23, v4
	v_mul_f32_e32 v5, v23, v5
	v_cvt_pk_bf16_f32 v68, v4, v5
	v_lshlrev_b32_e32 v4, 16, v69
	v_and_b32_e32 v5, 0xffff0000, v69
	v_mul_f32_e32 v4, v23, v4
	v_mul_f32_e32 v5, v23, v5
	v_cvt_pk_bf16_f32 v69, v4, v5
	v_lshlrev_b32_e32 v4, 16, v70
	v_and_b32_e32 v5, 0xffff0000, v70
	v_mul_f32_e32 v4, v23, v4
	v_mul_f32_e32 v5, v23, v5
	v_cvt_pk_bf16_f32 v70, v4, v5
	v_lshlrev_b32_e32 v4, 16, v71
	v_and_b32_e32 v5, 0xffff0000, v71
	v_mul_f32_e32 v4, v23, v4
	v_mul_f32_e32 v5, v23, v5
	v_cvt_pk_bf16_f32 v71, v4, v5
	global_store_dwordx4 v25, v[68:71], s[54:55] offset:3072
.Lgn_fast_done:
	s_mov_b64 s[36:37], -1
	s_branch .LBB0_394

; #define GAS __attribute__((address_space(1)))
; __device__ __forceinline__ gws_t launder_s(const void* p0) { unsigned char* p = (unsigned char*)p0; asm volatile("" : "+s"(p)); return (gws_t)p; }
; __device__ __forceinline__ int launder_v(int v) { asm volatile("" : "+v"(v)); return v; }
; __device__ __forceinline__ int grid_x() { int g = (int)gridDim.x; asm volatile("" : "+s"(g)); return g; }
; __device__ __forceinline__ float wave_sum(float v) {
; #pragma unroll
;     for (int o = 1; o < 64; o <<= 1) v += __shfl_xor(v, o);
;     return v;
; __device__ __forceinline__ void phase_gnorm(const Params& P, int seg) {
;     GAS bf16* ypre = (GAS bf16*)(launder_s(P.ws) + WS_YPRE);
;     const int tidl = launder_v(threadIdx.x); const int lane = tidl & 63, gw = blockIdx.x * 8 + (tidl >> 6), NGW = grid_x() * 8;
;     const int nrows = (seg == 0) ? RS + 16 : RS;
;     for (int rr = gw; rr < nrows; rr += NGW) { const int row = (rr < RS) ? rr : rr + 48; GAS bf16* p = ypre + (size_t)row * DINNER + lane * 8;
.LBB0_391:
	s_or_b64 exec, exec, s[0:1]
	s_mov_b64 s[0:1], s[80:81]
	s_waitcnt lgkmcnt(0)
	v_mov_b32_e32 v4, v172
	s_and_b64 s[14:15], s[36:37], exec
	s_barrier
	s_cmp_eq_u32 s82, 0x100
	s_cbranch_scc1 .Lgn_fast
	s_and_b64 s[14:15], s[36:37], exec
	v_readlane_b32 s9, v252, 40
	v_ashrrev_i32_e32 v5, 6, v4
	s_movk_i32 s14, 0x2010
	v_add_u32_e32 v20, s9, v5
	s_cselect_b32 s14, s14, 0x2000
	s_mov_b32 s9, s82
	v_cmp_gt_i32_e32 vcc, s14, v20
	s_and_saveexec_b64 s[36:37], vcc
	s_cbranch_execz .LBB0_394
	v_lshlrev_b32_e32 v4, 4, v4
	v_and_b32_e32 v174, 0x3f0, v4
	v_lshl_add_u64 v[4:5], s[0:1], 0, v[174:175]
	s_mov_b64 s[0:1], 0x304f1000
	v_lshl_add_u64 v[16:17], v[4:5], 0, s[0:1]
	v_and_b32_e32 v4, 64, v173
	v_add_u32_e32 v4, 64, v4
	v_xor_b32_e32 v5, 1, v173
	v_cmp_lt_i32_e32 vcc, v5, v4
	s_lshl_b32 s15, s9, 3
	s_mov_b64 s[40:41], 0
	v_cndmask_b32_e32 v5, v173, v5, vcc
	v_lshlrev_b32_e32 v21, 2, v5
	v_xor_b32_e32 v5, 2, v173
	v_cmp_lt_i32_e32 vcc, v5, v4
	s_nop 1
	v_cndmask_b32_e32 v5, v173, v5, vcc
	v_lshlrev_b32_e32 v22, 2, v5
	v_xor_b32_e32 v5, 4, v173
	v_cmp_lt_i32_e32 vcc, v5, v4
	s_nop 1
	v_cndmask_b32_e32 v5, v173, v5, vcc
	v_lshlrev_b32_e32 v23, 2, v5
	v_xor_b32_e32 v5, 8, v173
	v_cmp_lt_i32_e32 vcc, v5, v4
	s_nop 1
	v_cndmask_b32_e32 v5, v173, v5, vcc
	v_lshlrev_b32_e32 v24, 2, v5
	v_xor_b32_e32 v5, 16, v173
	v_cmp_lt_i32_e32 vcc, v5, v4
	s_nop 1
	v_cndmask_b32_e32 v5, v173, v5, vcc
	v_lshlrev_b32_e32 v25, 2, v5
	v_xor_b32_e32 v5, 32, v173
	v_cmp_lt_i32_e32 vcc, v5, v4
	s_nop 1
	v_cndmask_b32_e32 v4, v173, v5, vcc
	v_lshlrev_b32_e32 v26, 2, v4
